# layer-1 memory attention: hand-scheduled unit body (LDS operand reads issued 2-4 steps ahead of their MFMAs, max via max3 chain), HGRN loads interleaved into the preparation loop
# speedup vs baseline: 1.0020x; 1.0012x over previous
.LBB0_577:
	s_mov_b32 s13, 0xff61b1e6
	v_add_u32_e32 v150, 0x9000, v122
	v_add_u32_e32 v151, 0x9000, v123
	v_add_u32_e32 v152, 0x9000, v124
	v_add_u32_e32 v153, 0x9000, v125
	ds_read_b128 v[200:203], v128
	ds_read_b128 v[204:207], v128 offset:64
	ds_read_b128 v[208:211], v128 offset:2304
	ds_read_b128 v[212:215], v128 offset:2368
	ds_read_b128 v[216:219], v128 offset:4608
	ds_read_b128 v[220:223], v128 offset:4672
	ds_read_b128 v[224:227], v128 offset:6912
	ds_read_b128 v[228:231], v128 offset:6976
	s_waitcnt vmcnt(10)
	s_waitcnt lgkmcnt(4)
	v_mfma_f32_16x16x32_bf16 v[44:47], v[200:203], v[108:111], 0
	v_mfma_f32_16x16x32_bf16 v[48:51], v[208:211], v[108:111], 0
	v_mfma_f32_16x16x32_bf16 v[44:47], v[204:207], v[60:63], v[44:47]
	v_mfma_f32_16x16x32_bf16 v[48:51], v[212:215], v[60:63], v[48:51]
	ds_read_b128 v[200:203], v128 offset:9216
	ds_read_b128 v[204:207], v128 offset:9280
	ds_read_b128 v[208:211], v128 offset:11520
	ds_read_b128 v[212:215], v128 offset:11584
	s_waitcnt lgkmcnt(4)
	v_mfma_f32_16x16x32_bf16 v[52:55], v[216:219], v[108:111], 0
	v_mfma_f32_16x16x32_bf16 v[56:59], v[224:227], v[108:111], 0
	v_mfma_f32_16x16x32_bf16 v[52:55], v[220:223], v[60:63], v[52:55]
	v_mfma_f32_16x16x32_bf16 v[56:59], v[228:231], v[60:63], v[56:59]
	ds_read_b128 v[216:219], v128 offset:13824
	ds_read_b128 v[220:223], v128 offset:13888
	ds_read_b128 v[224:227], v128 offset:16128
	ds_read_b128 v[228:231], v128 offset:16192
	s_waitcnt lgkmcnt(4)
	v_mfma_f32_16x16x32_bf16 v[64:67], v[200:203], v[108:111], 0
	v_mfma_f32_16x16x32_bf16 v[68:71], v[208:211], v[108:111], 0
	v_mfma_f32_16x16x32_bf16 v[64:67], v[204:207], v[60:63], v[64:67]
	v_mfma_f32_16x16x32_bf16 v[68:71], v[212:215], v[60:63], v[68:71]
	ds_read_b128 v[200:203], v128 offset:18432
	ds_read_b128 v[204:207], v128 offset:18496
	ds_read_b128 v[208:211], v128 offset:20736
	ds_read_b128 v[212:215], v128 offset:20800
	s_waitcnt lgkmcnt(4)
	v_mfma_f32_16x16x32_bf16 v[72:75], v[216:219], v[108:111], 0
	v_mfma_f32_16x16x32_bf16 v[76:79], v[224:227], v[108:111], 0
	v_mfma_f32_16x16x32_bf16 v[72:75], v[220:223], v[60:63], v[72:75]
	v_mfma_f32_16x16x32_bf16 v[76:79], v[228:231], v[60:63], v[76:79]
	ds_read_b128 v[216:219], v128 offset:23040
	ds_read_b128 v[220:223], v128 offset:23104
	ds_read_b128 v[224:227], v128 offset:25344
	ds_read_b128 v[228:231], v128 offset:25408
	s_waitcnt lgkmcnt(4)
	v_mfma_f32_16x16x32_bf16 v[80:83], v[200:203], v[108:111], 0
	v_mfma_f32_16x16x32_bf16 v[84:87], v[208:211], v[108:111], 0
	v_mfma_f32_16x16x32_bf16 v[80:83], v[204:207], v[60:63], v[80:83]
	v_mfma_f32_16x16x32_bf16 v[84:87], v[212:215], v[60:63], v[84:87]
	ds_read_b128 v[200:203], v128 offset:27648
	ds_read_b128 v[204:207], v128 offset:27712
	ds_read_b128 v[208:211], v128 offset:29952
	ds_read_b128 v[212:215], v128 offset:30016
	s_waitcnt lgkmcnt(4)
	v_mfma_f32_16x16x32_bf16 v[88:91], v[216:219], v[108:111], 0
	v_mfma_f32_16x16x32_bf16 v[92:95], v[224:227], v[108:111], 0
	v_mfma_f32_16x16x32_bf16 v[88:91], v[220:223], v[60:63], v[88:91]
	v_mfma_f32_16x16x32_bf16 v[92:95], v[228:231], v[60:63], v[92:95]
	ds_read_b128 v[216:219], v128 offset:32256
	ds_read_b128 v[220:223], v128 offset:32320
	ds_read_b128 v[224:227], v128 offset:34560
	ds_read_b128 v[228:231], v128 offset:34624
	s_waitcnt lgkmcnt(4)
	v_mfma_f32_16x16x32_bf16 v[96:99], v[200:203], v[108:111], 0
	v_mfma_f32_16x16x32_bf16 v[100:103], v[208:211], v[108:111], 0
	v_mfma_f32_16x16x32_bf16 v[96:99], v[204:207], v[60:63], v[96:99]
	v_mfma_f32_16x16x32_bf16 v[100:103], v[212:215], v[60:63], v[100:103]
	s_waitcnt lgkmcnt(0)
	v_mfma_f32_16x16x32_bf16 v[104:107], v[216:219], v[108:111], 0
	v_mfma_f32_16x16x32_bf16 v[130:133], v[224:227], v[108:111], 0
	v_mfma_f32_16x16x32_bf16 v[104:107], v[220:223], v[60:63], v[104:107]
	v_mfma_f32_16x16x32_bf16 v[130:133], v[228:231], v[60:63], v[130:133]
	s_nop 7
	v_max3_f32 v154, v44, v45, s13
	v_max3_f32 v154, v46, v47, v154
	v_max3_f32 v154, v48, v49, v154
	v_max3_f32 v154, v50, v51, v154
	v_max3_f32 v154, v52, v53, v154
	v_max3_f32 v154, v54, v55, v154
	v_max3_f32 v154, v56, v57, v154
	v_max3_f32 v154, v58, v59, v154
	v_max3_f32 v154, v64, v65, v154
	v_max3_f32 v154, v66, v67, v154
	v_max3_f32 v154, v68, v69, v154
	v_max3_f32 v154, v70, v71, v154
	v_max3_f32 v154, v72, v73, v154
	v_max3_f32 v154, v74, v75, v154
	v_max3_f32 v154, v76, v77, v154
	v_max3_f32 v154, v78, v79, v154
	v_max3_f32 v154, v80, v81, v154
	v_max3_f32 v154, v82, v83, v154
	v_max3_f32 v154, v84, v85, v154
	v_max3_f32 v154, v86, v87, v154
	v_max3_f32 v154, v88, v89, v154
	v_max3_f32 v154, v90, v91, v154
	v_max3_f32 v154, v92, v93, v154
	v_max3_f32 v154, v94, v95, v154
	v_max3_f32 v154, v96, v97, v154
	v_max3_f32 v154, v98, v99, v154
	v_max3_f32 v154, v100, v101, v154
	v_max3_f32 v154, v102, v103, v154
	v_max3_f32 v154, v104, v105, v154
	v_max3_f32 v154, v106, v107, v154
	v_max3_f32 v154, v130, v131, v154
	v_max3_f32 v154, v132, v133, v154
	ds_bpermute_b32 v155, v126, v154
	s_waitcnt lgkmcnt(0)
	v_max_f32_e32 v154, v154, v155
	ds_bpermute_b32 v155, v127, v154
	s_waitcnt lgkmcnt(0)
	v_max_f32_e32 v154, v154, v155
	v_sub_f32_e32 v44, v44, v154
	v_exp_f32_e32 v44, v44
	v_sub_f32_e32 v45, v45, v154
	v_exp_f32_e32 v45, v45
	v_add_f32_e32 v172, 0, v44
	v_sub_f32_e32 v46, v46, v154
	v_exp_f32_e32 v46, v46
	v_add_f32_e32 v172, v45, v172
	v_sub_f32_e32 v47, v47, v154
	v_exp_f32_e32 v47, v47
	v_add_f32_e32 v172, v46, v172
	v_sub_f32_e32 v48, v48, v154
	v_exp_f32_e32 v48, v48
	v_add_f32_e32 v172, v47, v172
	v_sub_f32_e32 v49, v49, v154
	v_exp_f32_e32 v49, v49
	v_add_f32_e32 v172, v48, v172
	v_sub_f32_e32 v50, v50, v154
	v_exp_f32_e32 v50, v50
	v_add_f32_e32 v172, v49, v172
	v_sub_f32_e32 v51, v51, v154
	v_exp_f32_e32 v51, v51
	v_add_f32_e32 v172, v50, v172
	v_sub_f32_e32 v52, v52, v154
	v_exp_f32_e32 v52, v52
	v_add_f32_e32 v172, v51, v172
	v_sub_f32_e32 v53, v53, v154
	v_exp_f32_e32 v53, v53
	v_add_f32_e32 v172, v52, v172
	v_sub_f32_e32 v54, v54, v154
	v_exp_f32_e32 v54, v54
	v_add_f32_e32 v172, v53, v172
	v_sub_f32_e32 v55, v55, v154
	v_exp_f32_e32 v55, v55
	v_add_f32_e32 v172, v54, v172
	v_sub_f32_e32 v56, v56, v154
	v_exp_f32_e32 v56, v56
	v_add_f32_e32 v172, v55, v172
	v_sub_f32_e32 v57, v57, v154
	v_exp_f32_e32 v57, v57
	v_add_f32_e32 v172, v56, v172
	v_sub_f32_e32 v58, v58, v154
	v_exp_f32_e32 v58, v58
	v_add_f32_e32 v172, v57, v172
	v_sub_f32_e32 v59, v59, v154
	v_exp_f32_e32 v59, v59
	v_add_f32_e32 v172, v58, v172
	v_sub_f32_e32 v64, v64, v154
	v_exp_f32_e32 v64, v64
	v_add_f32_e32 v172, v59, v172
	v_sub_f32_e32 v65, v65, v154
	v_exp_f32_e32 v65, v65
	v_add_f32_e32 v172, v64, v172
	v_sub_f32_e32 v66, v66, v154
	v_exp_f32_e32 v66, v66
	v_add_f32_e32 v172, v65, v172
	v_sub_f32_e32 v67, v67, v154
	v_exp_f32_e32 v67, v67
	v_add_f32_e32 v172, v66, v172
	v_sub_f32_e32 v68, v68, v154
	v_exp_f32_e32 v68, v68
	v_add_f32_e32 v172, v67, v172
	v_sub_f32_e32 v69, v69, v154
	v_exp_f32_e32 v69, v69
	v_add_f32_e32 v172, v68, v172
	v_sub_f32_e32 v70, v70, v154
	v_exp_f32_e32 v70, v70
	v_add_f32_e32 v172, v69, v172
	v_sub_f32_e32 v71, v71, v154
	v_exp_f32_e32 v71, v71
	v_add_f32_e32 v172, v70, v172
	v_sub_f32_e32 v72, v72, v154
	v_exp_f32_e32 v72, v72
	v_add_f32_e32 v172, v71, v172
	v_sub_f32_e32 v73, v73, v154
	v_exp_f32_e32 v73, v73
	v_add_f32_e32 v172, v72, v172
	v_sub_f32_e32 v74, v74, v154
	v_exp_f32_e32 v74, v74
	v_add_f32_e32 v172, v73, v172
	v_sub_f32_e32 v75, v75, v154
	v_exp_f32_e32 v75, v75
	v_add_f32_e32 v172, v74, v172
	v_sub_f32_e32 v76, v76, v154
	v_exp_f32_e32 v76, v76
	v_add_f32_e32 v172, v75, v172
	v_sub_f32_e32 v77, v77, v154
	v_exp_f32_e32 v77, v77
	v_add_f32_e32 v172, v76, v172
	v_sub_f32_e32 v78, v78, v154
	v_exp_f32_e32 v78, v78
	v_add_f32_e32 v172, v77, v172
	v_sub_f32_e32 v79, v79, v154
	v_exp_f32_e32 v79, v79
	v_add_f32_e32 v172, v78, v172
	v_sub_f32_e32 v80, v80, v154
	v_exp_f32_e32 v80, v80
	v_add_f32_e32 v172, v79, v172
	v_sub_f32_e32 v81, v81, v154
	v_exp_f32_e32 v81, v81
	v_add_f32_e32 v172, v80, v172
	v_sub_f32_e32 v82, v82, v154
	v_exp_f32_e32 v82, v82
	v_add_f32_e32 v172, v81, v172
	v_sub_f32_e32 v83, v83, v154
	v_exp_f32_e32 v83, v83
	v_add_f32_e32 v172, v82, v172
	v_sub_f32_e32 v84, v84, v154
	v_exp_f32_e32 v84, v84
	v_add_f32_e32 v172, v83, v172
	v_sub_f32_e32 v85, v85, v154
	v_exp_f32_e32 v85, v85
	v_add_f32_e32 v172, v84, v172
	v_sub_f32_e32 v86, v86, v154
	v_exp_f32_e32 v86, v86
	v_add_f32_e32 v172, v85, v172
	v_sub_f32_e32 v87, v87, v154
	v_exp_f32_e32 v87, v87
	v_add_f32_e32 v172, v86, v172
	v_sub_f32_e32 v88, v88, v154
	v_exp_f32_e32 v88, v88
	v_add_f32_e32 v172, v87, v172
	v_sub_f32_e32 v89, v89, v154
	v_exp_f32_e32 v89, v89
	v_add_f32_e32 v172, v88, v172
	v_sub_f32_e32 v90, v90, v154
	v_exp_f32_e32 v90, v90
	v_add_f32_e32 v172, v89, v172
	v_sub_f32_e32 v91, v91, v154
	v_exp_f32_e32 v91, v91
	v_add_f32_e32 v172, v90, v172
	v_sub_f32_e32 v92, v92, v154
	v_exp_f32_e32 v92, v92
	v_add_f32_e32 v172, v91, v172
	v_sub_f32_e32 v93, v93, v154
	v_exp_f32_e32 v93, v93
	v_add_f32_e32 v172, v92, v172
	v_sub_f32_e32 v94, v94, v154
	v_exp_f32_e32 v94, v94
	v_add_f32_e32 v172, v93, v172
	v_sub_f32_e32 v95, v95, v154
	v_exp_f32_e32 v95, v95
	v_add_f32_e32 v172, v94, v172
	v_sub_f32_e32 v96, v96, v154
	v_exp_f32_e32 v96, v96
	v_add_f32_e32 v172, v95, v172
	v_sub_f32_e32 v97, v97, v154
	v_exp_f32_e32 v97, v97
	v_add_f32_e32 v172, v96, v172
	v_sub_f32_e32 v98, v98, v154
	v_exp_f32_e32 v98, v98
	v_add_f32_e32 v172, v97, v172
	v_sub_f32_e32 v99, v99, v154
	v_exp_f32_e32 v99, v99
	v_add_f32_e32 v172, v98, v172
	v_sub_f32_e32 v100, v100, v154
	v_exp_f32_e32 v100, v100
	v_add_f32_e32 v172, v99, v172
	v_sub_f32_e32 v101, v101, v154
	v_exp_f32_e32 v101, v101
	v_add_f32_e32 v172, v100, v172
	v_sub_f32_e32 v102, v102, v154
	v_exp_f32_e32 v102, v102
	v_add_f32_e32 v172, v101, v172
	v_sub_f32_e32 v103, v103, v154
	v_exp_f32_e32 v103, v103
	v_add_f32_e32 v172, v102, v172
	v_sub_f32_e32 v104, v104, v154
	v_exp_f32_e32 v104, v104
	v_add_f32_e32 v172, v103, v172
	v_sub_f32_e32 v105, v105, v154
	v_exp_f32_e32 v105, v105
	v_add_f32_e32 v172, v104, v172
	v_sub_f32_e32 v106, v106, v154
	v_exp_f32_e32 v106, v106
	v_add_f32_e32 v172, v105, v172
	v_sub_f32_e32 v107, v107, v154
	v_exp_f32_e32 v107, v107
	v_add_f32_e32 v172, v106, v172
	v_sub_f32_e32 v130, v130, v154
	v_exp_f32_e32 v130, v130
	v_add_f32_e32 v172, v107, v172
	v_sub_f32_e32 v131, v131, v154
	v_exp_f32_e32 v131, v131
	v_add_f32_e32 v172, v130, v172
	v_sub_f32_e32 v132, v132, v154
	v_exp_f32_e32 v132, v132
	v_add_f32_e32 v172, v131, v172
	v_sub_f32_e32 v133, v133, v154
	v_exp_f32_e32 v133, v133
	v_add_f32_e32 v172, v132, v172
	s_nop 0
	v_add_f32_e32 v172, v133, v172
	ds_bpermute_b32 v155, v126, v172
	s_waitcnt lgkmcnt(0)
	v_add_f32_e32 v172, v172, v155
	ds_bpermute_b32 v155, v127, v172
	s_waitcnt lgkmcnt(0)
	v_add_f32_e32 v172, v172, v155
	ds_read2_b64 v[200:203], v150 offset0:0 offset1:4
	ds_read2_b64 v[204:207], v151 offset0:0 offset1:4
	ds_read2_b64 v[208:211], v152 offset0:0 offset1:4
	ds_read2_b64 v[212:215], v153 offset0:0 offset1:4
	ds_read2_b64 v[216:219], v150 offset0:8 offset1:12
	ds_read2_b64 v[220:223], v151 offset0:8 offset1:12
	ds_read2_b64 v[224:227], v152 offset0:8 offset1:12
	ds_read2_b64 v[228:231], v153 offset0:8 offset1:12
	v_cvt_pk_bf16_f32 v44, v44, v45
	v_cvt_pk_bf16_f32 v45, v46, v47
	v_cvt_pk_bf16_f32 v46, v48, v49
	v_cvt_pk_bf16_f32 v47, v50, v51
	v_cvt_pk_bf16_f32 v52, v52, v53
	v_cvt_pk_bf16_f32 v53, v54, v55
	v_cvt_pk_bf16_f32 v54, v56, v57
	v_cvt_pk_bf16_f32 v55, v58, v59
	s_waitcnt lgkmcnt(4)
	s_nop 1
	v_mfma_f32_16x16x32_bf16 v[134:137], v[200:203], v[44:47], 0
	v_mfma_f32_16x16x32_bf16 v[138:141], v[204:207], v[44:47], 0
	v_mfma_f32_16x16x32_bf16 v[142:145], v[208:211], v[44:47], 0
	v_mfma_f32_16x16x32_bf16 v[146:149], v[212:215], v[44:47], 0
	ds_read2_b64 v[200:203], v150 offset0:16 offset1:20
	ds_read2_b64 v[204:207], v151 offset0:16 offset1:20
	ds_read2_b64 v[208:211], v152 offset0:16 offset1:20
	ds_read2_b64 v[212:215], v153 offset0:16 offset1:20
	v_cvt_pk_bf16_f32 v64, v64, v65
	v_cvt_pk_bf16_f32 v65, v66, v67
	v_cvt_pk_bf16_f32 v66, v68, v69
	v_cvt_pk_bf16_f32 v67, v70, v71
	s_waitcnt lgkmcnt(4)
	s_nop 1
	v_mfma_f32_16x16x32_bf16 v[134:137], v[216:219], v[52:55], v[134:137]
	v_mfma_f32_16x16x32_bf16 v[138:141], v[220:223], v[52:55], v[138:141]
	v_mfma_f32_16x16x32_bf16 v[142:145], v[224:227], v[52:55], v[142:145]
	v_mfma_f32_16x16x32_bf16 v[146:149], v[228:231], v[52:55], v[146:149]
	ds_read2_b64 v[216:219], v150 offset0:24 offset1:28
	ds_read2_b64 v[220:223], v151 offset0:24 offset1:28
	ds_read2_b64 v[224:227], v152 offset0:24 offset1:28
	ds_read2_b64 v[228:231], v153 offset0:24 offset1:28
	v_cvt_pk_bf16_f32 v72, v72, v73
	v_cvt_pk_bf16_f32 v73, v74, v75
	v_cvt_pk_bf16_f32 v74, v76, v77
	v_cvt_pk_bf16_f32 v75, v78, v79
	s_waitcnt lgkmcnt(4)
	s_nop 1
	v_mfma_f32_16x16x32_bf16 v[134:137], v[200:203], v[64:67], v[134:137]
	v_mfma_f32_16x16x32_bf16 v[138:141], v[204:207], v[64:67], v[138:141]
	v_mfma_f32_16x16x32_bf16 v[142:145], v[208:211], v[64:67], v[142:145]
	v_mfma_f32_16x16x32_bf16 v[146:149], v[212:215], v[64:67], v[146:149]
	ds_read2_b64 v[200:203], v150 offset0:32 offset1:36
	ds_read2_b64 v[204:207], v151 offset0:32 offset1:36
	ds_read2_b64 v[208:211], v152 offset0:32 offset1:36
	ds_read2_b64 v[212:215], v153 offset0:32 offset1:36
	v_cvt_pk_bf16_f32 v80, v80, v81
	v_cvt_pk_bf16_f32 v81, v82, v83
	v_cvt_pk_bf16_f32 v82, v84, v85
	v_cvt_pk_bf16_f32 v83, v86, v87
	s_waitcnt lgkmcnt(4)
	s_nop 1
	v_mfma_f32_16x16x32_bf16 v[134:137], v[216:219], v[72:75], v[134:137]
	v_mfma_f32_16x16x32_bf16 v[138:141], v[220:223], v[72:75], v[138:141]
	v_mfma_f32_16x16x32_bf16 v[142:145], v[224:227], v[72:75], v[142:145]
	v_mfma_f32_16x16x32_bf16 v[146:149], v[228:231], v[72:75], v[146:149]
	ds_read2_b64 v[216:219], v150 offset0:40 offset1:44
	ds_read2_b64 v[220:223], v151 offset0:40 offset1:44
	ds_read2_b64 v[224:227], v152 offset0:40 offset1:44
	ds_read2_b64 v[228:231], v153 offset0:40 offset1:44
	v_cvt_pk_bf16_f32 v88, v88, v89
	v_cvt_pk_bf16_f32 v89, v90, v91
	v_cvt_pk_bf16_f32 v90, v92, v93
	v_cvt_pk_bf16_f32 v91, v94, v95
	s_waitcnt lgkmcnt(4)
	s_nop 1
	v_mfma_f32_16x16x32_bf16 v[134:137], v[200:203], v[80:83], v[134:137]
	v_mfma_f32_16x16x32_bf16 v[138:141], v[204:207], v[80:83], v[138:141]
	v_mfma_f32_16x16x32_bf16 v[142:145], v[208:211], v[80:83], v[142:145]
	v_mfma_f32_16x16x32_bf16 v[146:149], v[212:215], v[80:83], v[146:149]
	ds_read2_b64 v[200:203], v150 offset0:48 offset1:52
	ds_read2_b64 v[204:207], v151 offset0:48 offset1:52
	ds_read2_b64 v[208:211], v152 offset0:48 offset1:52
	ds_read2_b64 v[212:215], v153 offset0:48 offset1:52
	v_cvt_pk_bf16_f32 v96, v96, v97
	v_cvt_pk_bf16_f32 v97, v98, v99
	v_cvt_pk_bf16_f32 v98, v100, v101
	v_cvt_pk_bf16_f32 v99, v102, v103
	s_waitcnt lgkmcnt(4)
	s_nop 1
	v_mfma_f32_16x16x32_bf16 v[134:137], v[216:219], v[88:91], v[134:137]
	v_mfma_f32_16x16x32_bf16 v[138:141], v[220:223], v[88:91], v[138:141]
	v_mfma_f32_16x16x32_bf16 v[142:145], v[224:227], v[88:91], v[142:145]
	v_mfma_f32_16x16x32_bf16 v[146:149], v[228:231], v[88:91], v[146:149]
	ds_read2_b64 v[216:219], v150 offset0:56 offset1:60
	ds_read2_b64 v[220:223], v151 offset0:56 offset1:60
	ds_read2_b64 v[224:227], v152 offset0:56 offset1:60
	ds_read2_b64 v[228:231], v153 offset0:56 offset1:60
	v_cvt_pk_bf16_f32 v104, v104, v105
	v_cvt_pk_bf16_f32 v105, v106, v107
	v_cvt_pk_bf16_f32 v106, v130, v131
	v_cvt_pk_bf16_f32 v107, v132, v133
	s_waitcnt lgkmcnt(4)
	s_nop 1
	v_mfma_f32_16x16x32_bf16 v[134:137], v[200:203], v[96:99], v[134:137]
	v_mfma_f32_16x16x32_bf16 v[138:141], v[204:207], v[96:99], v[138:141]
	v_mfma_f32_16x16x32_bf16 v[142:145], v[208:211], v[96:99], v[142:145]
	v_mfma_f32_16x16x32_bf16 v[146:149], v[212:215], v[96:99], v[146:149]
	s_waitcnt lgkmcnt(0)
	s_nop 1
	v_mfma_f32_16x16x32_bf16 v[134:137], v[216:219], v[104:107], v[134:137]
	v_mfma_f32_16x16x32_bf16 v[138:141], v[220:223], v[104:107], v[138:141]
	v_mfma_f32_16x16x32_bf16 v[142:145], v[224:227], v[104:107], v[142:145]
	v_mfma_f32_16x16x32_bf16 v[146:149], v[228:231], v[104:107], v[146:149]
	v_div_scale_f32 v173, s[8:9], v172, v172, 1.0
	v_rcp_f32_e32 v175, v173
	s_nop 0
	v_fma_f32 v176, -v173, v175, 1.0
	v_fmac_f32_e32 v175, v176, v175
	v_div_scale_f32 v174, vcc, 1.0, v172, 1.0
	v_mul_f32_e32 v177, v174, v175
	v_fma_f32 v176, -v173, v177, v174
	v_fmac_f32_e32 v177, v176, v175
	v_fma_f32 v173, -v173, v177, v174
	v_div_fmas_f32 v173, v173, v175, v177
	v_div_fixup_f32 v180, v173, v172, 1.0
	v_lshlrev_b64 v[182:183], 11, v[116:117]
	v_lshl_add_u64 v[182:183], s[0:1], 0, v[182:183]
	v_lshl_add_u64 v[182:183], v[182:183], 0, s[36:37]
	v_lshl_add_u64 v[182:183], v[182:183], 0, v[2:3]
	v_mul_f32_e32 v134, v180, v134
	v_mul_f32_e32 v135, v180, v135
	v_mul_f32_e32 v136, v180, v136
	v_mul_f32_e32 v137, v180, v137
	v_cvt_pk_bf16_f32 v184, v134, v135
	v_cvt_pk_bf16_f32 v185, v136, v137
	s_nop 0
	global_store_dwordx2 v[182:183], v[184:185], off offset:1536
	v_mul_f32_e32 v138, v180, v138
	v_mul_f32_e32 v139, v180, v139
	v_mul_f32_e32 v140, v180, v140
	v_mul_f32_e32 v141, v180, v141
	v_cvt_pk_bf16_f32 v186, v138, v139
	v_cvt_pk_bf16_f32 v187, v140, v141
	s_nop 0
	global_store_dwordx2 v[182:183], v[186:187], off offset:1568
	v_mul_f32_e32 v142, v180, v142
	v_mul_f32_e32 v143, v180, v143
	v_mul_f32_e32 v144, v180, v144
	v_mul_f32_e32 v145, v180, v145
	v_cvt_pk_bf16_f32 v188, v142, v143
	v_cvt_pk_bf16_f32 v189, v144, v145
	s_nop 0
	global_store_dwordx2 v[182:183], v[188:189], off offset:1600
	v_mul_f32_e32 v146, v180, v146
	v_mul_f32_e32 v147, v180, v147
	v_mul_f32_e32 v148, v180, v148
	v_mul_f32_e32 v149, v180, v149
	v_cvt_pk_bf16_f32 v190, v146, v147
	v_cvt_pk_bf16_f32 v191, v148, v149
	s_nop 0
	global_store_dwordx2 v[182:183], v[190:191], off offset:1632
	ds_read_b128 v[200:203], v128
	ds_read_b128 v[204:207], v128 offset:64
	ds_read_b128 v[208:211], v128 offset:2304
	ds_read_b128 v[212:215], v128 offset:2368
	ds_read_b128 v[216:219], v128 offset:4608
	ds_read_b128 v[220:223], v128 offset:4672
	ds_read_b128 v[224:227], v128 offset:6912
	ds_read_b128 v[228:231], v128 offset:6976
	s_waitcnt vmcnt(12)
	s_waitcnt lgkmcnt(4)
	v_mfma_f32_16x16x32_bf16 v[44:47], v[200:203], v[40:43], 0
	v_mfma_f32_16x16x32_bf16 v[48:51], v[208:211], v[40:43], 0
	v_mfma_f32_16x16x32_bf16 v[44:47], v[204:207], v[36:39], v[44:47]
	v_mfma_f32_16x16x32_bf16 v[48:51], v[212:215], v[36:39], v[48:51]
	ds_read_b128 v[200:203], v128 offset:9216
	ds_read_b128 v[204:207], v128 offset:9280
	ds_read_b128 v[208:211], v128 offset:11520
	ds_read_b128 v[212:215], v128 offset:11584
	s_waitcnt lgkmcnt(4)
	v_mfma_f32_16x16x32_bf16 v[52:55], v[216:219], v[40:43], 0
	v_mfma_f32_16x16x32_bf16 v[56:59], v[224:227], v[40:43], 0
	v_mfma_f32_16x16x32_bf16 v[52:55], v[220:223], v[36:39], v[52:55]
	v_mfma_f32_16x16x32_bf16 v[56:59], v[228:231], v[36:39], v[56:59]
	ds_read_b128 v[216:219], v128 offset:13824
	ds_read_b128 v[220:223], v128 offset:13888
	ds_read_b128 v[224:227], v128 offset:16128
	ds_read_b128 v[228:231], v128 offset:16192
	s_waitcnt lgkmcnt(4)
	v_mfma_f32_16x16x32_bf16 v[64:67], v[200:203], v[40:43], 0
	v_mfma_f32_16x16x32_bf16 v[68:71], v[208:211], v[40:43], 0
	v_mfma_f32_16x16x32_bf16 v[64:67], v[204:207], v[36:39], v[64:67]
	v_mfma_f32_16x16x32_bf16 v[68:71], v[212:215], v[36:39], v[68:71]
	ds_read_b128 v[200:203], v128 offset:18432
	ds_read_b128 v[204:207], v128 offset:18496
	ds_read_b128 v[208:211], v128 offset:20736
	ds_read_b128 v[212:215], v128 offset:20800
	s_waitcnt lgkmcnt(4)
	v_mfma_f32_16x16x32_bf16 v[72:75], v[216:219], v[40:43], 0
	v_mfma_f32_16x16x32_bf16 v[76:79], v[224:227], v[40:43], 0
	v_mfma_f32_16x16x32_bf16 v[72:75], v[220:223], v[36:39], v[72:75]
	v_mfma_f32_16x16x32_bf16 v[76:79], v[228:231], v[36:39], v[76:79]
	ds_read_b128 v[216:219], v128 offset:23040
	ds_read_b128 v[220:223], v128 offset:23104
	ds_read_b128 v[224:227], v128 offset:25344
	ds_read_b128 v[228:231], v128 offset:25408
	s_waitcnt lgkmcnt(4)
	v_mfma_f32_16x16x32_bf16 v[80:83], v[200:203], v[40:43], 0
	v_mfma_f32_16x16x32_bf16 v[84:87], v[208:211], v[40:43], 0
	v_mfma_f32_16x16x32_bf16 v[80:83], v[204:207], v[36:39], v[80:83]
	v_mfma_f32_16x16x32_bf16 v[84:87], v[212:215], v[36:39], v[84:87]
	ds_read_b128 v[200:203], v128 offset:27648
	ds_read_b128 v[204:207], v128 offset:27712
	ds_read_b128 v[208:211], v128 offset:29952
	ds_read_b128 v[212:215], v128 offset:30016
	s_waitcnt lgkmcnt(4)
	v_mfma_f32_16x16x32_bf16 v[88:91], v[216:219], v[40:43], 0
	v_mfma_f32_16x16x32_bf16 v[92:95], v[224:227], v[40:43], 0
	v_mfma_f32_16x16x32_bf16 v[88:91], v[220:223], v[36:39], v[88:91]
	v_mfma_f32_16x16x32_bf16 v[92:95], v[228:231], v[36:39], v[92:95]
	ds_read_b128 v[216:219], v128 offset:32256
	ds_read_b128 v[220:223], v128 offset:32320
	ds_read_b128 v[224:227], v128 offset:34560
	ds_read_b128 v[228:231], v128 offset:34624
	s_waitcnt lgkmcnt(4)
	v_mfma_f32_16x16x32_bf16 v[96:99], v[200:203], v[40:43], 0
	v_mfma_f32_16x16x32_bf16 v[100:103], v[208:211], v[40:43], 0
	v_mfma_f32_16x16x32_bf16 v[96:99], v[204:207], v[36:39], v[96:99]
	v_mfma_f32_16x16x32_bf16 v[100:103], v[212:215], v[36:39], v[100:103]
	s_waitcnt lgkmcnt(0)
	v_mfma_f32_16x16x32_bf16 v[104:107], v[216:219], v[40:43], 0
	v_mfma_f32_16x16x32_bf16 v[130:133], v[224:227], v[40:43], 0
	v_mfma_f32_16x16x32_bf16 v[104:107], v[220:223], v[36:39], v[104:107]
	v_mfma_f32_16x16x32_bf16 v[130:133], v[228:231], v[36:39], v[130:133]
	s_nop 7
	v_max3_f32 v154, v44, v45, s13
	v_max3_f32 v154, v46, v47, v154
	v_max3_f32 v154, v48, v49, v154
	v_max3_f32 v154, v50, v51, v154
	v_max3_f32 v154, v52, v53, v154
	v_max3_f32 v154, v54, v55, v154
	v_max3_f32 v154, v56, v57, v154
	v_max3_f32 v154, v58, v59, v154
	v_max3_f32 v154, v64, v65, v154
	v_max3_f32 v154, v66, v67, v154
	v_max3_f32 v154, v68, v69, v154
	v_max3_f32 v154, v70, v71, v154
	v_max3_f32 v154, v72, v73, v154
	v_max3_f32 v154, v74, v75, v154
	v_max3_f32 v154, v76, v77, v154
	v_max3_f32 v154, v78, v79, v154
	v_max3_f32 v154, v80, v81, v154
	v_max3_f32 v154, v82, v83, v154
	v_max3_f32 v154, v84, v85, v154
	v_max3_f32 v154, v86, v87, v154
	v_max3_f32 v154, v88, v89, v154
	v_max3_f32 v154, v90, v91, v154
	v_max3_f32 v154, v92, v93, v154
	v_max3_f32 v154, v94, v95, v154
	v_max3_f32 v154, v96, v97, v154
	v_max3_f32 v154, v98, v99, v154
	v_max3_f32 v154, v100, v101, v154
	v_max3_f32 v154, v102, v103, v154
	v_max3_f32 v154, v104, v105, v154
	v_max3_f32 v154, v106, v107, v154
	v_max3_f32 v154, v130, v131, v154
	v_max3_f32 v154, v132, v133, v154
	ds_bpermute_b32 v155, v126, v154
	s_waitcnt lgkmcnt(0)
	v_max_f32_e32 v154, v154, v155
	ds_bpermute_b32 v155, v127, v154
	s_waitcnt lgkmcnt(0)
	v_max_f32_e32 v154, v154, v155
	v_sub_f32_e32 v44, v44, v154
	v_exp_f32_e32 v44, v44
	v_sub_f32_e32 v45, v45, v154
	v_exp_f32_e32 v45, v45
	v_add_f32_e32 v172, 0, v44
	v_sub_f32_e32 v46, v46, v154
	v_exp_f32_e32 v46, v46
	v_add_f32_e32 v172, v45, v172
	v_sub_f32_e32 v47, v47, v154
	v_exp_f32_e32 v47, v47
	v_add_f32_e32 v172, v46, v172
	v_sub_f32_e32 v48, v48, v154
	v_exp_f32_e32 v48, v48
	v_add_f32_e32 v172, v47, v172
	v_sub_f32_e32 v49, v49, v154
	v_exp_f32_e32 v49, v49
	v_add_f32_e32 v172, v48, v172
	v_sub_f32_e32 v50, v50, v154
	v_exp_f32_e32 v50, v50
	v_add_f32_e32 v172, v49, v172
	v_sub_f32_e32 v51, v51, v154
	v_exp_f32_e32 v51, v51
	v_add_f32_e32 v172, v50, v172
	v_sub_f32_e32 v52, v52, v154
	v_exp_f32_e32 v52, v52
	v_add_f32_e32 v172, v51, v172
	v_sub_f32_e32 v53, v53, v154
	v_exp_f32_e32 v53, v53
	v_add_f32_e32 v172, v52, v172
	v_sub_f32_e32 v54, v54, v154
	v_exp_f32_e32 v54, v54
	v_add_f32_e32 v172, v53, v172
	v_sub_f32_e32 v55, v55, v154
	v_exp_f32_e32 v55, v55
	v_add_f32_e32 v172, v54, v172
	v_sub_f32_e32 v56, v56, v154
	v_exp_f32_e32 v56, v56
	v_add_f32_e32 v172, v55, v172
	v_sub_f32_e32 v57, v57, v154
	v_exp_f32_e32 v57, v57
	v_add_f32_e32 v172, v56, v172
	v_sub_f32_e32 v58, v58, v154
	v_exp_f32_e32 v58, v58
	v_add_f32_e32 v172, v57, v172
	v_sub_f32_e32 v59, v59, v154
	v_exp_f32_e32 v59, v59
	v_add_f32_e32 v172, v58, v172
	v_sub_f32_e32 v64, v64, v154
	v_exp_f32_e32 v64, v64
	v_add_f32_e32 v172, v59, v172
	v_sub_f32_e32 v65, v65, v154
	v_exp_f32_e32 v65, v65
	v_add_f32_e32 v172, v64, v172
	v_sub_f32_e32 v66, v66, v154
	v_exp_f32_e32 v66, v66
	v_add_f32_e32 v172, v65, v172
	v_sub_f32_e32 v67, v67, v154
	v_exp_f32_e32 v67, v67
	v_add_f32_e32 v172, v66, v172
	v_sub_f32_e32 v68, v68, v154
	v_exp_f32_e32 v68, v68
	v_add_f32_e32 v172, v67, v172
	v_sub_f32_e32 v69, v69, v154
	v_exp_f32_e32 v69, v69
	v_add_f32_e32 v172, v68, v172
	v_sub_f32_e32 v70, v70, v154
	v_exp_f32_e32 v70, v70
	v_add_f32_e32 v172, v69, v172
	v_sub_f32_e32 v71, v71, v154
	v_exp_f32_e32 v71, v71
	v_add_f32_e32 v172, v70, v172
	v_sub_f32_e32 v72, v72, v154
	v_exp_f32_e32 v72, v72
	v_add_f32_e32 v172, v71, v172
	v_sub_f32_e32 v73, v73, v154
	v_exp_f32_e32 v73, v73
	v_add_f32_e32 v172, v72, v172
	v_sub_f32_e32 v74, v74, v154
	v_exp_f32_e32 v74, v74
	v_add_f32_e32 v172, v73, v172
	v_sub_f32_e32 v75, v75, v154
	v_exp_f32_e32 v75, v75
	v_add_f32_e32 v172, v74, v172
	v_sub_f32_e32 v76, v76, v154
	v_exp_f32_e32 v76, v76
	v_add_f32_e32 v172, v75, v172
	v_sub_f32_e32 v77, v77, v154
	v_exp_f32_e32 v77, v77
	v_add_f32_e32 v172, v76, v172
	v_sub_f32_e32 v78, v78, v154
	v_exp_f32_e32 v78, v78
	v_add_f32_e32 v172, v77, v172
	v_sub_f32_e32 v79, v79, v154
	v_exp_f32_e32 v79, v79
	v_add_f32_e32 v172, v78, v172
	v_sub_f32_e32 v80, v80, v154
	v_exp_f32_e32 v80, v80
	v_add_f32_e32 v172, v79, v172
	v_sub_f32_e32 v81, v81, v154
	v_exp_f32_e32 v81, v81
	v_add_f32_e32 v172, v80, v172
	v_sub_f32_e32 v82, v82, v154
	v_exp_f32_e32 v82, v82
	v_add_f32_e32 v172, v81, v172
	v_sub_f32_e32 v83, v83, v154
	v_exp_f32_e32 v83, v83
	v_add_f32_e32 v172, v82, v172
	v_sub_f32_e32 v84, v84, v154
	v_exp_f32_e32 v84, v84
	v_add_f32_e32 v172, v83, v172
	v_sub_f32_e32 v85, v85, v154
	v_exp_f32_e32 v85, v85
	v_add_f32_e32 v172, v84, v172
	v_sub_f32_e32 v86, v86, v154
	v_exp_f32_e32 v86, v86
	v_add_f32_e32 v172, v85, v172
	v_sub_f32_e32 v87, v87, v154
	v_exp_f32_e32 v87, v87
	v_add_f32_e32 v172, v86, v172
	v_sub_f32_e32 v88, v88, v154
	v_exp_f32_e32 v88, v88
	v_add_f32_e32 v172, v87, v172
	v_sub_f32_e32 v89, v89, v154
	v_exp_f32_e32 v89, v89
	v_add_f32_e32 v172, v88, v172
	v_sub_f32_e32 v90, v90, v154
	v_exp_f32_e32 v90, v90
	v_add_f32_e32 v172, v89, v172
	v_sub_f32_e32 v91, v91, v154
	v_exp_f32_e32 v91, v91
	v_add_f32_e32 v172, v90, v172
	v_sub_f32_e32 v92, v92, v154
	v_exp_f32_e32 v92, v92
	v_add_f32_e32 v172, v91, v172
	v_sub_f32_e32 v93, v93, v154
	v_exp_f32_e32 v93, v93
	v_add_f32_e32 v172, v92, v172
	v_sub_f32_e32 v94, v94, v154
	v_exp_f32_e32 v94, v94
	v_add_f32_e32 v172, v93, v172
	v_sub_f32_e32 v95, v95, v154
	v_exp_f32_e32 v95, v95
	v_add_f32_e32 v172, v94, v172
	v_sub_f32_e32 v96, v96, v154
	v_exp_f32_e32 v96, v96
	v_add_f32_e32 v172, v95, v172
	v_sub_f32_e32 v97, v97, v154
	v_exp_f32_e32 v97, v97
	v_add_f32_e32 v172, v96, v172
	v_sub_f32_e32 v98, v98, v154
	v_exp_f32_e32 v98, v98
	v_add_f32_e32 v172, v97, v172
	v_sub_f32_e32 v99, v99, v154
	v_exp_f32_e32 v99, v99
	v_add_f32_e32 v172, v98, v172
	v_sub_f32_e32 v100, v100, v154
	v_exp_f32_e32 v100, v100
	v_add_f32_e32 v172, v99, v172
	v_sub_f32_e32 v101, v101, v154
	v_exp_f32_e32 v101, v101
	v_add_f32_e32 v172, v100, v172
	v_sub_f32_e32 v102, v102, v154
	v_exp_f32_e32 v102, v102
	v_add_f32_e32 v172, v101, v172
	v_sub_f32_e32 v103, v103, v154
	v_exp_f32_e32 v103, v103
	v_add_f32_e32 v172, v102, v172
	v_sub_f32_e32 v104, v104, v154
	v_exp_f32_e32 v104, v104
	v_add_f32_e32 v172, v103, v172
	v_sub_f32_e32 v105, v105, v154
	v_exp_f32_e32 v105, v105
	v_add_f32_e32 v172, v104, v172
	v_sub_f32_e32 v106, v106, v154
	v_exp_f32_e32 v106, v106
	v_add_f32_e32 v172, v105, v172
	v_sub_f32_e32 v107, v107, v154
	v_exp_f32_e32 v107, v107
	v_add_f32_e32 v172, v106, v172
	v_sub_f32_e32 v130, v130, v154
	v_exp_f32_e32 v130, v130
	v_add_f32_e32 v172, v107, v172
	v_sub_f32_e32 v131, v131, v154
	v_exp_f32_e32 v131, v131
	v_add_f32_e32 v172, v130, v172
	v_sub_f32_e32 v132, v132, v154
	v_exp_f32_e32 v132, v132
	v_add_f32_e32 v172, v131, v172
	v_sub_f32_e32 v133, v133, v154
	v_exp_f32_e32 v133, v133
	v_add_f32_e32 v172, v132, v172
	s_nop 0
	v_add_f32_e32 v172, v133, v172
	ds_bpermute_b32 v155, v126, v172
	s_waitcnt lgkmcnt(0)
	v_add_f32_e32 v172, v172, v155
	ds_bpermute_b32 v155, v127, v172
	s_waitcnt lgkmcnt(0)
	v_add_f32_e32 v172, v172, v155
	ds_read2_b64 v[200:203], v150 offset0:0 offset1:4
	ds_read2_b64 v[204:207], v151 offset0:0 offset1:4
	ds_read2_b64 v[208:211], v152 offset0:0 offset1:4
	ds_read2_b64 v[212:215], v153 offset0:0 offset1:4
	ds_read2_b64 v[216:219], v150 offset0:8 offset1:12
	ds_read2_b64 v[220:223], v151 offset0:8 offset1:12
	ds_read2_b64 v[224:227], v152 offset0:8 offset1:12
	ds_read2_b64 v[228:231], v153 offset0:8 offset1:12
	v_cvt_pk_bf16_f32 v44, v44, v45
	v_cvt_pk_bf16_f32 v45, v46, v47
	v_cvt_pk_bf16_f32 v46, v48, v49
	v_cvt_pk_bf16_f32 v47, v50, v51
	v_cvt_pk_bf16_f32 v52, v52, v53
	v_cvt_pk_bf16_f32 v53, v54, v55
	v_cvt_pk_bf16_f32 v54, v56, v57
	v_cvt_pk_bf16_f32 v55, v58, v59
	s_waitcnt lgkmcnt(4)
	s_nop 1
	v_mfma_f32_16x16x32_bf16 v[134:137], v[200:203], v[44:47], 0
	v_mfma_f32_16x16x32_bf16 v[138:141], v[204:207], v[44:47], 0
	v_mfma_f32_16x16x32_bf16 v[142:145], v[208:211], v[44:47], 0
	v_mfma_f32_16x16x32_bf16 v[146:149], v[212:215], v[44:47], 0
	ds_read2_b64 v[200:203], v150 offset0:16 offset1:20
	ds_read2_b64 v[204:207], v151 offset0:16 offset1:20
	ds_read2_b64 v[208:211], v152 offset0:16 offset1:20
	ds_read2_b64 v[212:215], v153 offset0:16 offset1:20
	v_cvt_pk_bf16_f32 v64, v64, v65
	v_cvt_pk_bf16_f32 v65, v66, v67
	v_cvt_pk_bf16_f32 v66, v68, v69
	v_cvt_pk_bf16_f32 v67, v70, v71
	s_waitcnt lgkmcnt(4)
	s_nop 1
	v_mfma_f32_16x16x32_bf16 v[134:137], v[216:219], v[52:55], v[134:137]
	v_mfma_f32_16x16x32_bf16 v[138:141], v[220:223], v[52:55], v[138:141]
	v_mfma_f32_16x16x32_bf16 v[142:145], v[224:227], v[52:55], v[142:145]
	v_mfma_f32_16x16x32_bf16 v[146:149], v[228:231], v[52:55], v[146:149]
	ds_read2_b64 v[216:219], v150 offset0:24 offset1:28
	ds_read2_b64 v[220:223], v151 offset0:24 offset1:28
	ds_read2_b64 v[224:227], v152 offset0:24 offset1:28
	ds_read2_b64 v[228:231], v153 offset0:24 offset1:28
	v_cvt_pk_bf16_f32 v72, v72, v73
	v_cvt_pk_bf16_f32 v73, v74, v75
	v_cvt_pk_bf16_f32 v74, v76, v77
	v_cvt_pk_bf16_f32 v75, v78, v79
	s_waitcnt lgkmcnt(4)
	s_nop 1
	v_mfma_f32_16x16x32_bf16 v[134:137], v[200:203], v[64:67], v[134:137]
	v_mfma_f32_16x16x32_bf16 v[138:141], v[204:207], v[64:67], v[138:141]
	v_mfma_f32_16x16x32_bf16 v[142:145], v[208:211], v[64:67], v[142:145]
	v_mfma_f32_16x16x32_bf16 v[146:149], v[212:215], v[64:67], v[146:149]
	ds_read2_b64 v[200:203], v150 offset0:32 offset1:36
	ds_read2_b64 v[204:207], v151 offset0:32 offset1:36
	ds_read2_b64 v[208:211], v152 offset0:32 offset1:36
	ds_read2_b64 v[212:215], v153 offset0:32 offset1:36
	v_cvt_pk_bf16_f32 v80, v80, v81
	v_cvt_pk_bf16_f32 v81, v82, v83
	v_cvt_pk_bf16_f32 v82, v84, v85
	v_cvt_pk_bf16_f32 v83, v86, v87
	s_waitcnt lgkmcnt(4)
	s_nop 1
	v_mfma_f32_16x16x32_bf16 v[134:137], v[216:219], v[72:75], v[134:137]
	v_mfma_f32_16x16x32_bf16 v[138:141], v[220:223], v[72:75], v[138:141]
	v_mfma_f32_16x16x32_bf16 v[142:145], v[224:227], v[72:75], v[142:145]
	v_mfma_f32_16x16x32_bf16 v[146:149], v[228:231], v[72:75], v[146:149]
	ds_read2_b64 v[216:219], v150 offset0:40 offset1:44
	ds_read2_b64 v[220:223], v151 offset0:40 offset1:44
	ds_read2_b64 v[224:227], v152 offset0:40 offset1:44
	ds_read2_b64 v[228:231], v153 offset0:40 offset1:44
	v_cvt_pk_bf16_f32 v88, v88, v89
	v_cvt_pk_bf16_f32 v89, v90, v91
	v_cvt_pk_bf16_f32 v90, v92, v93
	v_cvt_pk_bf16_f32 v91, v94, v95
	s_waitcnt lgkmcnt(4)
	s_nop 1
	v_mfma_f32_16x16x32_bf16 v[134:137], v[200:203], v[80:83], v[134:137]
	v_mfma_f32_16x16x32_bf16 v[138:141], v[204:207], v[80:83], v[138:141]
	v_mfma_f32_16x16x32_bf16 v[142:145], v[208:211], v[80:83], v[142:145]
	v_mfma_f32_16x16x32_bf16 v[146:149], v[212:215], v[80:83], v[146:149]
	ds_read2_b64 v[200:203], v150 offset0:48 offset1:52
	ds_read2_b64 v[204:207], v151 offset0:48 offset1:52
	ds_read2_b64 v[208:211], v152 offset0:48 offset1:52
	ds_read2_b64 v[212:215], v153 offset0:48 offset1:52
	v_cvt_pk_bf16_f32 v96, v96, v97
	v_cvt_pk_bf16_f32 v97, v98, v99
	v_cvt_pk_bf16_f32 v98, v100, v101
	v_cvt_pk_bf16_f32 v99, v102, v103
	s_waitcnt lgkmcnt(4)
	s_nop 1
	v_mfma_f32_16x16x32_bf16 v[134:137], v[216:219], v[88:91], v[134:137]
	v_mfma_f32_16x16x32_bf16 v[138:141], v[220:223], v[88:91], v[138:141]
	v_mfma_f32_16x16x32_bf16 v[142:145], v[224:227], v[88:91], v[142:145]
	v_mfma_f32_16x16x32_bf16 v[146:149], v[228:231], v[88:91], v[146:149]
	ds_read2_b64 v[216:219], v150 offset0:56 offset1:60
	ds_read2_b64 v[220:223], v151 offset0:56 offset1:60
	ds_read2_b64 v[224:227], v152 offset0:56 offset1:60
	ds_read2_b64 v[228:231], v153 offset0:56 offset1:60
	v_cvt_pk_bf16_f32 v104, v104, v105
	v_cvt_pk_bf16_f32 v105, v106, v107
	v_cvt_pk_bf16_f32 v106, v130, v131
	v_cvt_pk_bf16_f32 v107, v132, v133
	s_waitcnt lgkmcnt(4)
	s_nop 1
	v_mfma_f32_16x16x32_bf16 v[134:137], v[200:203], v[96:99], v[134:137]
	v_mfma_f32_16x16x32_bf16 v[138:141], v[204:207], v[96:99], v[138:141]
	v_mfma_f32_16x16x32_bf16 v[142:145], v[208:211], v[96:99], v[142:145]
	v_mfma_f32_16x16x32_bf16 v[146:149], v[212:215], v[96:99], v[146:149]
	s_waitcnt lgkmcnt(0)
	s_nop 1
	v_mfma_f32_16x16x32_bf16 v[134:137], v[216:219], v[104:107], v[134:137]
	v_mfma_f32_16x16x32_bf16 v[138:141], v[220:223], v[104:107], v[138:141]
	v_mfma_f32_16x16x32_bf16 v[142:145], v[224:227], v[104:107], v[142:145]
	v_mfma_f32_16x16x32_bf16 v[146:149], v[228:231], v[104:107], v[146:149]
	v_div_scale_f32 v173, s[8:9], v172, v172, 1.0
	v_rcp_f32_e32 v175, v173
	s_nop 0
	v_fma_f32 v176, -v173, v175, 1.0
	v_fmac_f32_e32 v175, v176, v175
	v_div_scale_f32 v174, vcc, 1.0, v172, 1.0
	v_mul_f32_e32 v177, v174, v175
	v_fma_f32 v176, -v173, v177, v174
	v_fmac_f32_e32 v177, v176, v175
	v_fma_f32 v173, -v173, v177, v174
	v_div_fmas_f32 v173, v173, v175, v177
	v_div_fixup_f32 v180, v173, v172, 1.0
	v_lshlrev_b64 v[182:183], 11, v[114:115]
	v_lshl_add_u64 v[182:183], s[0:1], 0, v[182:183]
	v_lshl_add_u64 v[182:183], v[182:183], 0, s[36:37]
	v_lshl_add_u64 v[182:183], v[182:183], 0, v[2:3]
	v_mul_f32_e32 v134, v180, v134
	v_mul_f32_e32 v135, v180, v135
	v_mul_f32_e32 v136, v180, v136
	v_mul_f32_e32 v137, v180, v137
	v_cvt_pk_bf16_f32 v184, v134, v135
	v_cvt_pk_bf16_f32 v185, v136, v137
	s_nop 0
	global_store_dwordx2 v[182:183], v[184:185], off offset:1536
	v_mul_f32_e32 v138, v180, v138
	v_mul_f32_e32 v139, v180, v139
	v_mul_f32_e32 v140, v180, v140
	v_mul_f32_e32 v141, v180, v141
	v_cvt_pk_bf16_f32 v186, v138, v139
	v_cvt_pk_bf16_f32 v187, v140, v141
	s_nop 0
	global_store_dwordx2 v[182:183], v[186:187], off offset:1568
	v_mul_f32_e32 v142, v180, v142
	v_mul_f32_e32 v143, v180, v143
	v_mul_f32_e32 v144, v180, v144
	v_mul_f32_e32 v145, v180, v145
	v_cvt_pk_bf16_f32 v188, v142, v143
	v_cvt_pk_bf16_f32 v189, v144, v145
	s_nop 0
	global_store_dwordx2 v[182:183], v[188:189], off offset:1600
	v_mul_f32_e32 v146, v180, v146
	v_mul_f32_e32 v147, v180, v147
	v_mul_f32_e32 v148, v180, v148
	v_mul_f32_e32 v149, v180, v149
	v_cvt_pk_bf16_f32 v190, v146, v147
	v_cvt_pk_bf16_f32 v191, v148, v149
	s_nop 0
	global_store_dwordx2 v[182:183], v[190:191], off offset:1632
	s_mov_b32 s13, s12
	s_andn2_b64 vcc, exec, s[6:7]
	s_barrier
	s_cbranch_vccz .LBB0_582

.Lhg_loop:
	s_cmp_gt_u32 s18, 3
	s_cbranch_scc1 .Lhg_bfirst_2
	ds_read_b128 v[144:147], v5 offset:8704
	ds_read_b128 v[148:151], v5 offset:13056
	ds_read_b128 v[152:155], v5 offset:0
	ds_read_b128 v[172:175], v5 offset:4352
	ds_read_b128 v[176:179], v5 offset:8768
	ds_read_b128 v[180:183], v5 offset:13120
	ds_read_b128 v[184:187], v5 offset:64
	ds_read_b128 v[188:191], v5 offset:4416
	ds_read_b128 v[200:203], v5 offset:8832
	ds_read_b128 v[204:207], v5 offset:13184
	ds_read_b128 v[208:211], v5 offset:128
	ds_read_b128 v[212:215], v5 offset:4480
	s_waitcnt lgkmcnt(8)
	v_mfma_f32_16x16x32_bf16 v[124:127], v[144:147], v[152:155], 0
	v_mfma_f32_16x16x32_bf16 v[128:131], v[144:147], v[172:175], 0
	v_mfma_f32_16x16x32_bf16 v[132:135], v[148:151], v[172:175], 0
	ds_read_b128 v[216:219], v5 offset:8896
	ds_read_b128 v[220:223], v5 offset:13248
	ds_read_b128 v[224:227], v5 offset:192
	ds_read_b128 v[228:231], v5 offset:4544
	s_waitcnt lgkmcnt(8)
	v_mfma_f32_16x16x32_bf16 v[124:127], v[176:179], v[184:187], v[124:127]
	v_mfma_f32_16x16x32_bf16 v[128:131], v[176:179], v[188:191], v[128:131]
	v_mfma_f32_16x16x32_bf16 v[132:135], v[180:183], v[188:191], v[132:135]
	ds_read_b64 v[144:145], v6 offset:0
	ds_read_b64 v[146:147], v6 offset:32
	ds_read_b64 v[148:149], v6 offset:4352
	ds_read_b64 v[150:151], v6 offset:4384
	s_waitcnt lgkmcnt(8)
	v_mfma_f32_16x16x32_bf16 v[124:127], v[200:203], v[208:211], v[124:127]
	v_mfma_f32_16x16x32_bf16 v[128:131], v[200:203], v[212:215], v[128:131]
	v_mfma_f32_16x16x32_bf16 v[132:135], v[204:207], v[212:215], v[132:135]
	ds_read_b64 v[152:153], v6 offset:64
	ds_read_b64 v[154:155], v6 offset:96
	ds_read_b64 v[172:173], v6 offset:4416
	ds_read_b64 v[174:175], v6 offset:4448
	s_waitcnt lgkmcnt(8)
	v_mfma_f32_16x16x32_bf16 v[124:127], v[216:219], v[224:227], v[124:127]
	v_mfma_f32_16x16x32_bf16 v[128:131], v[216:219], v[228:231], v[128:131]
	v_mfma_f32_16x16x32_bf16 v[132:135], v[220:223], v[228:231], v[132:135]
	ds_read_b64 v[176:177], v6 offset:128
	ds_read_b64 v[178:179], v6 offset:160
	ds_read_b64 v[180:181], v6 offset:4480
	ds_read_b64 v[182:183], v6 offset:4512
	v_cvt_pk_bf16_f32 v232, v92, v93
	v_cvt_pk_bf16_f32 v233, v94, v95
	v_cvt_pk_bf16_f32 v234, v96, v97
	v_cvt_pk_bf16_f32 v235, v98, v99
	s_waitcnt lgkmcnt(8)
	s_nop 1
	v_mfma_f32_16x16x32_bf16 v[136:139], v[144:147], v[232:235], 0
	v_mfma_f32_16x16x32_bf16 v[140:143], v[148:151], v[232:235], 0
	ds_read_b64 v[184:185], v6 offset:192
	ds_read_b64 v[186:187], v6 offset:224
	ds_read_b64 v[188:189], v6 offset:4544
	ds_read_b64 v[190:191], v6 offset:4576
	v_cvt_pk_bf16_f32 v232, v100, v101
	v_cvt_pk_bf16_f32 v233, v102, v103
	v_cvt_pk_bf16_f32 v234, v104, v105
	v_cvt_pk_bf16_f32 v235, v106, v107
	s_waitcnt lgkmcnt(8)
	s_nop 1
	v_mfma_f32_16x16x32_bf16 v[136:139], v[152:155], v[232:235], v[136:139]
	v_mfma_f32_16x16x32_bf16 v[140:143], v[172:175], v[232:235], v[140:143]
	ds_read_b64 v[236:237], v7 offset:27648
	ds_read_b64 v[238:239], v7 offset:27680
	ds_read_b128 v[200:203], v8 offset:27648
	v_cvt_pk_bf16_f32 v232, v108, v109
	v_cvt_pk_bf16_f32 v233, v110, v111
	v_cvt_pk_bf16_f32 v234, v112, v113
	v_cvt_pk_bf16_f32 v235, v114, v115
	s_waitcnt lgkmcnt(7)
	s_nop 1
	v_mfma_f32_16x16x32_bf16 v[136:139], v[176:179], v[232:235], v[136:139]
	v_mfma_f32_16x16x32_bf16 v[140:143], v[180:183], v[232:235], v[140:143]
	ds_read_b128 v[204:207], v9 offset:17408
	ds_read_b128 v[208:211], v10 offset:37888
	v_cvt_pk_bf16_f32 v232, v116, v117
	v_cvt_pk_bf16_f32 v233, v118, v119
	v_cvt_pk_bf16_f32 v234, v120, v121
	v_cvt_pk_bf16_f32 v235, v122, v123
	s_waitcnt lgkmcnt(5)
	s_nop 1
	v_mfma_f32_16x16x32_bf16 v[136:139], v[184:187], v[232:235], v[136:139]
	v_mfma_f32_16x16x32_bf16 v[140:143], v[188:191], v[232:235], v[140:143]
	ds_read_b128 v[212:215], v9 offset:18688
	ds_read_b128 v[216:219], v10 offset:37952
	v_cndmask_b32_e64 v124, 0, v124, s[40:41]
	v_cndmask_b32_e64 v132, 0, v132, s[40:41]
	v_cndmask_b32_e64 v125, 0, v125, s[42:43]
	v_cndmask_b32_e64 v133, 0, v133, s[42:43]
	v_cndmask_b32_e64 v126, 0, v126, s[44:45]
	v_cndmask_b32_e64 v134, 0, v134, s[44:45]
	v_cndmask_b32_e64 v127, 0, v127, s[46:47]
	v_cndmask_b32_e64 v135, 0, v135, s[46:47]
	v_cvt_pk_bf16_f32 v124, v124, v125
	v_cvt_pk_bf16_f32 v125, v126, v127
	v_mov_b32_e32 v126, 0
	v_mov_b32_e32 v127, 0
	v_cvt_pk_bf16_f32 v128, v128, v129
	v_cvt_pk_bf16_f32 v129, v130, v131
	v_cvt_pk_bf16_f32 v130, v132, v133
	v_cvt_pk_bf16_f32 v131, v134, v135
	s_waitcnt lgkmcnt(4)
	s_nop 1
	v_mfma_f32_16x16x32_bf16 v[136:139], v[124:127], v[236:239], v[136:139]
	v_mfma_f32_16x16x32_bf16 v[140:143], v[128:131], v[236:239], v[140:143]
	ds_read_b128 v[220:223], v9 offset:19968
	ds_read_b128 v[224:227], v10 offset:38016
	ds_read_b128 v[228:231], v9 offset:21248
	ds_read_b128 v[144:147], v10 offset:38080
	s_waitcnt lgkmcnt(6)
	v_pk_mul_f32 v[92:93], v[92:93], v[208:209]
	v_pk_mul_f32 v[94:95], v[94:95], v[210:211]
	s_nop 1
	v_mfma_f32_16x16x32_bf16 v[92:95], v[204:207], v[200:203], v[92:95]
	ds_read_b128 v[152:155], v9 offset:22528
	ds_read_b128 v[172:175], v10 offset:38144
	s_waitcnt lgkmcnt(6)
	v_pk_mul_f32 v[96:97], v[96:97], v[216:217]
	v_pk_mul_f32 v[98:99], v[98:99], v[218:219]
	s_nop 1
	v_mfma_f32_16x16x32_bf16 v[96:99], v[212:215], v[200:203], v[96:99]
	ds_read_b128 v[176:179], v9 offset:23808
	ds_read_b128 v[180:183], v10 offset:38208
	s_waitcnt lgkmcnt(6)
	v_pk_mul_f32 v[100:101], v[100:101], v[224:225]
	v_pk_mul_f32 v[102:103], v[102:103], v[226:227]
	s_nop 1
	v_mfma_f32_16x16x32_bf16 v[100:103], v[220:223], v[200:203], v[100:103]
	ds_read_b128 v[184:187], v9 offset:25088
	ds_read_b128 v[188:191], v10 offset:38272
	s_waitcnt lgkmcnt(6)
	v_pk_mul_f32 v[104:105], v[104:105], v[144:145]
	v_pk_mul_f32 v[106:107], v[106:107], v[146:147]
	s_nop 1
	v_mfma_f32_16x16x32_bf16 v[104:107], v[228:231], v[200:203], v[104:107]
	ds_read_b128 v[204:207], v9 offset:26368
	ds_read_b128 v[208:211], v10 offset:38336
	s_waitcnt lgkmcnt(6)
	v_pk_mul_f32 v[108:109], v[108:109], v[172:173]
	v_pk_mul_f32 v[110:111], v[110:111], v[174:175]
	s_nop 1
	v_mfma_f32_16x16x32_bf16 v[108:111], v[152:155], v[200:203], v[108:111]
	s_waitcnt lgkmcnt(4)
	v_pk_mul_f32 v[112:113], v[112:113], v[180:181]
	v_pk_mul_f32 v[114:115], v[114:115], v[182:183]
	s_nop 1
	v_mfma_f32_16x16x32_bf16 v[112:115], v[176:179], v[200:203], v[112:115]
	s_waitcnt lgkmcnt(2)
	v_pk_mul_f32 v[116:117], v[116:117], v[188:189]
	v_pk_mul_f32 v[118:119], v[118:119], v[190:191]
	s_nop 1
	v_mfma_f32_16x16x32_bf16 v[116:119], v[184:187], v[200:203], v[116:119]
	s_waitcnt lgkmcnt(0)
	v_pk_mul_f32 v[120:121], v[120:121], v[208:209]
	v_pk_mul_f32 v[122:123], v[122:123], v[210:211]
	s_nop 1
	v_mfma_f32_16x16x32_bf16 v[120:123], v[204:207], v[200:203], v[120:123]
	ds_write_b32 v11, v136
	ds_write_b32 v11, v140 offset:8448
	ds_write_b32 v11, v137 offset:528
	ds_write_b32 v11, v141 offset:8976
	ds_write_b32 v11, v138 offset:1056
	ds_write_b32 v11, v142 offset:9504
	ds_write_b32 v11, v139 offset:1584
	ds_write_b32 v11, v143 offset:10032
	s_waitcnt vmcnt(9)
	ds_read_b32 v200, v0 offset:57344
	ds_read_b32 v201, v0 offset:57856
	ds_read_b32 v202, v0 offset:58368
	ds_read_b32 v203, v0 offset:58880
	v_lshl_or_b32 v220, v69, 16, v68
	v_lshl_or_b32 v221, v71, 16, v70
	v_lshl_or_b32 v222, v73, 16, v72
	v_lshl_or_b32 v223, v75, 16, v74
	ds_write_b128 v4, v[220:223] offset:27648
	s_waitcnt lgkmcnt(1)
	v_mul_f32_e32 v204, v21, v200
	v_fmac_f32_e32 v204, v22, v201
	v_fmac_f32_e32 v204, v23, v202
	v_add_f32_e32 v205, v200, v201
	v_add_f32_e32 v205, v205, v202
	v_add_f32_e32 v205, v205, v203
	global_load_dword v84, v14, s[4:5]
	global_load_ushort v36, v18, s[8:9]
	global_load_ushort v44, v18, s[10:11]
	v_mov_b32_e32 v219, v52
	v_add_f32_e32 v218, v204, v219
	v_mul_f32_e32 v207, 0x3fb8aa3b, v52
	v_exp_f32_e32 v207, v207
	v_lshlrev_b32_e32 v209, 16, v60
	v_sub_f32_e32 v208, 1.0, v207
	v_mul_f32_e32 v207, 0x3fb8aa3b, v218
	v_exp_f32_e32 v207, v207
	v_add_f32_e32 v206, v218, v24
	v_mul_f32_e32 v224, v209, v207
	v_mul_f32_e32 v206, 0x3fb8aa3b, v206
	v_exp_f32_e32 v206, v206
	v_sub_f32_e32 v207, v205, v218
	v_mul_f32_e32 v52, v209, v206
	v_mul_f32_e32 v207, 0x3fb8aa3b, v207
	v_exp_f32_e32 v207, v207
	v_min_f32_e64 v206, -v218, s29
	v_mul_f32_e32 v210, v208, v207
	v_mul_f32_e32 v206, 0x3fb8aa3b, v206
	v_exp_f32_e32 v206, v206
	s_nop 0
	v_mul_f32_e32 v232, v208, v206
	global_load_dword v85, v14, s[4:5] offset:3072
	global_load_ushort v37, v18, s[8:9] offset:1536
	global_load_ushort v45, v18, s[10:11] offset:1536
	v_add_f32_e32 v219, v219, v53
	v_add_f32_e32 v218, v204, v219
	v_mul_f32_e32 v207, 0x3fb8aa3b, v53
	v_exp_f32_e32 v207, v207
	v_lshlrev_b32_e32 v209, 16, v61
	v_sub_f32_e32 v208, 1.0, v207
	v_mul_f32_e32 v207, 0x3fb8aa3b, v218
	v_exp_f32_e32 v207, v207
	v_add_f32_e32 v206, v218, v24
	v_mul_f32_e32 v225, v209, v207
	v_mul_f32_e32 v206, 0x3fb8aa3b, v206
	v_exp_f32_e32 v206, v206
	v_sub_f32_e32 v207, v205, v218
	v_mul_f32_e32 v53, v209, v206
	v_mul_f32_e32 v207, 0x3fb8aa3b, v207
	v_exp_f32_e32 v207, v207
	v_min_f32_e64 v206, -v218, s29
	v_mul_f32_e32 v211, v208, v207
	v_mul_f32_e32 v206, 0x3fb8aa3b, v206
	v_exp_f32_e32 v206, v206
	s_nop 0
	v_mul_f32_e32 v233, v208, v206
	global_load_dword v86, v15, s[4:5]
	global_load_ushort v38, v18, s[8:9] offset:3072
	global_load_ushort v46, v18, s[10:11] offset:3072
	v_add_f32_e32 v219, v219, v54
	v_add_f32_e32 v218, v204, v219
	v_mul_f32_e32 v207, 0x3fb8aa3b, v54
	v_exp_f32_e32 v207, v207
	v_lshlrev_b32_e32 v209, 16, v62
	v_sub_f32_e32 v208, 1.0, v207
	v_mul_f32_e32 v207, 0x3fb8aa3b, v218
	v_exp_f32_e32 v207, v207
	v_add_f32_e32 v206, v218, v24
	v_mul_f32_e32 v226, v209, v207
	v_mul_f32_e32 v206, 0x3fb8aa3b, v206
	v_exp_f32_e32 v206, v206
	v_sub_f32_e32 v207, v205, v218
	v_mul_f32_e32 v54, v209, v206
	v_mul_f32_e32 v207, 0x3fb8aa3b, v207
	v_exp_f32_e32 v207, v207
	v_min_f32_e64 v206, -v218, s29
	v_mul_f32_e32 v212, v208, v207
	v_mul_f32_e32 v206, 0x3fb8aa3b, v206
	v_exp_f32_e32 v206, v206
	s_nop 0
	v_mul_f32_e32 v234, v208, v206
	global_load_dword v87, v15, s[4:5] offset:3072
	global_load_ushort v39, v19, s[8:9]
	global_load_ushort v47, v19, s[10:11]
	v_add_f32_e32 v219, v219, v55
	v_add_f32_e32 v218, v204, v219
	v_mul_f32_e32 v207, 0x3fb8aa3b, v55
	v_exp_f32_e32 v207, v207
	v_lshlrev_b32_e32 v209, 16, v63
	v_sub_f32_e32 v208, 1.0, v207
	v_mul_f32_e32 v207, 0x3fb8aa3b, v218
	v_exp_f32_e32 v207, v207
	v_add_f32_e32 v206, v218, v24
	v_mul_f32_e32 v227, v209, v207
	v_mul_f32_e32 v206, 0x3fb8aa3b, v206
	v_exp_f32_e32 v206, v206
	v_sub_f32_e32 v207, v205, v218
	v_mul_f32_e32 v55, v209, v206
	v_mul_f32_e32 v207, 0x3fb8aa3b, v207
	v_exp_f32_e32 v207, v207
	v_min_f32_e64 v206, -v218, s29
	v_mul_f32_e32 v213, v208, v207
	v_mul_f32_e32 v206, 0x3fb8aa3b, v206
	v_exp_f32_e32 v206, v206
	s_nop 0
	v_mul_f32_e32 v235, v208, v206
	global_load_dword v88, v16, s[4:5]
	global_load_ushort v40, v19, s[8:9] offset:1536
	global_load_ushort v48, v19, s[10:11] offset:1536
	v_add_f32_e32 v219, v219, v56
	v_add_f32_e32 v218, v204, v219
	v_mul_f32_e32 v207, 0x3fb8aa3b, v56
	v_exp_f32_e32 v207, v207
	v_lshlrev_b32_e32 v209, 16, v64
	v_sub_f32_e32 v208, 1.0, v207
	v_mul_f32_e32 v207, 0x3fb8aa3b, v218
	v_exp_f32_e32 v207, v207
	v_add_f32_e32 v206, v218, v24
	v_mul_f32_e32 v228, v209, v207
	v_mul_f32_e32 v206, 0x3fb8aa3b, v206
	v_exp_f32_e32 v206, v206
	v_sub_f32_e32 v207, v205, v218
	v_mul_f32_e32 v56, v209, v206
	v_mul_f32_e32 v207, 0x3fb8aa3b, v207
	v_exp_f32_e32 v207, v207
	v_min_f32_e64 v206, -v218, s29
	v_mul_f32_e32 v214, v208, v207
	v_mul_f32_e32 v206, 0x3fb8aa3b, v206
	v_exp_f32_e32 v206, v206
	s_nop 0
	v_mul_f32_e32 v236, v208, v206
	global_load_dword v89, v16, s[4:5] offset:3072
	global_load_ushort v41, v19, s[8:9] offset:3072
	global_load_ushort v49, v19, s[10:11] offset:3072
	v_add_f32_e32 v219, v219, v57
	v_add_f32_e32 v218, v204, v219
	v_mul_f32_e32 v207, 0x3fb8aa3b, v57
	v_exp_f32_e32 v207, v207
	v_lshlrev_b32_e32 v209, 16, v65
	v_sub_f32_e32 v208, 1.0, v207
	v_mul_f32_e32 v207, 0x3fb8aa3b, v218
	v_exp_f32_e32 v207, v207
	v_add_f32_e32 v206, v218, v24
	v_mul_f32_e32 v229, v209, v207
	v_mul_f32_e32 v206, 0x3fb8aa3b, v206
	v_exp_f32_e32 v206, v206
	v_sub_f32_e32 v207, v205, v218
	v_mul_f32_e32 v57, v209, v206
	v_mul_f32_e32 v207, 0x3fb8aa3b, v207
	v_exp_f32_e32 v207, v207
	v_min_f32_e64 v206, -v218, s29
	v_mul_f32_e32 v215, v208, v207
	v_mul_f32_e32 v206, 0x3fb8aa3b, v206
	v_exp_f32_e32 v206, v206
	s_nop 0
	v_mul_f32_e32 v237, v208, v206
	global_load_dword v90, v17, s[4:5]
	global_load_ushort v42, v20, s[8:9]
	global_load_ushort v50, v20, s[10:11]
	v_add_f32_e32 v219, v219, v58
	v_add_f32_e32 v218, v204, v219
	v_mul_f32_e32 v207, 0x3fb8aa3b, v58
	v_exp_f32_e32 v207, v207
	v_lshlrev_b32_e32 v209, 16, v66
	v_sub_f32_e32 v208, 1.0, v207
	v_mul_f32_e32 v207, 0x3fb8aa3b, v218
	v_exp_f32_e32 v207, v207
	v_add_f32_e32 v206, v218, v24
	v_mul_f32_e32 v230, v209, v207
	v_mul_f32_e32 v206, 0x3fb8aa3b, v206
	v_exp_f32_e32 v206, v206
	v_sub_f32_e32 v207, v205, v218
	v_mul_f32_e32 v58, v209, v206
	v_mul_f32_e32 v207, 0x3fb8aa3b, v207
	v_exp_f32_e32 v207, v207
	v_min_f32_e64 v206, -v218, s29
	v_mul_f32_e32 v216, v208, v207
	v_mul_f32_e32 v206, 0x3fb8aa3b, v206
	v_exp_f32_e32 v206, v206
	s_nop 0
	v_mul_f32_e32 v238, v208, v206
	global_load_dword v91, v17, s[4:5] offset:3072
	global_load_ushort v43, v20, s[8:9] offset:1536
	global_load_ushort v51, v20, s[10:11] offset:1536
	v_add_f32_e32 v219, v219, v59
	v_add_f32_e32 v218, v204, v219
	v_mul_f32_e32 v207, 0x3fb8aa3b, v59
	v_exp_f32_e32 v207, v207
	v_lshlrev_b32_e32 v209, 16, v67
	v_sub_f32_e32 v208, 1.0, v207
	v_mul_f32_e32 v207, 0x3fb8aa3b, v218
	v_exp_f32_e32 v207, v207
	v_add_f32_e32 v206, v218, v24
	v_mul_f32_e32 v231, v209, v207
	v_mul_f32_e32 v206, 0x3fb8aa3b, v206
	v_exp_f32_e32 v206, v206
	v_sub_f32_e32 v207, v205, v218
	v_mul_f32_e32 v59, v209, v206
	v_mul_f32_e32 v207, 0x3fb8aa3b, v207
	v_exp_f32_e32 v207, v207
	v_min_f32_e64 v206, -v218, s29
	v_mul_f32_e32 v217, v208, v207
	v_mul_f32_e32 v206, 0x3fb8aa3b, v206
	v_exp_f32_e32 v206, v206
	s_nop 0
	v_mul_f32_e32 v239, v208, v206
	v_cvt_pk_bf16_f32 v224, v224, v225
	ds_write_b16 v2, v224
	ds_write_b16_d16_hi v2, v224 offset:272
	v_cvt_pk_bf16_f32 v232, v232, v233
	ds_write_b16 v2, v232 offset:8704
	ds_write_b16_d16_hi v2, v232 offset:8976
	v_cvt_pk_bf16_f32 v226, v226, v227
	ds_write_b16 v2, v226 offset:544
	ds_write_b16_d16_hi v2, v226 offset:816
	v_cvt_pk_bf16_f32 v234, v234, v235
	ds_write_b16 v2, v234 offset:9248
	ds_write_b16_d16_hi v2, v234 offset:9520
	v_cvt_pk_bf16_f32 v228, v228, v229
	ds_write_b16 v2, v228 offset:1088
	ds_write_b16_d16_hi v2, v228 offset:1360
	v_cvt_pk_bf16_f32 v236, v236, v237
	ds_write_b16 v2, v236 offset:9792
	ds_write_b16_d16_hi v2, v236 offset:10064
	v_cvt_pk_bf16_f32 v230, v230, v231
	ds_write_b16 v2, v230 offset:1632
	ds_write_b16_d16_hi v2, v230 offset:1904
	v_cvt_pk_bf16_f32 v238, v238, v239
	ds_write_b16 v2, v238 offset:10336
	ds_write_b16_d16_hi v2, v238 offset:10608
	v_cvt_pk_bf16_f32 v210, v210, v211
	v_cvt_pk_bf16_f32 v211, v212, v213
	v_cvt_pk_bf16_f32 v212, v214, v215
	v_cvt_pk_bf16_f32 v213, v216, v217
	ds_write_b128 v4, v[210:213] offset:17408
	v_cvt_pk_bf16_f32 v52, v52, v53
	v_cvt_pk_bf16_f32 v54, v54, v55
	v_cvt_pk_bf16_f32 v56, v56, v57
	v_cvt_pk_bf16_f32 v58, v58, v59
	global_store_short v18, v52, s[12:13]
	global_store_short_d16_hi v18, v52, s[12:13] offset:1536
	global_store_short v18, v54, s[12:13] offset:3072
	global_store_short_d16_hi v19, v54, s[12:13]
	global_store_short v19, v56, s[12:13] offset:1536
	global_store_short_d16_hi v19, v56, s[12:13] offset:3072
	global_store_short v20, v58, s[12:13]
	global_store_short_d16_hi v20, v58, s[12:13] offset:1536
	s_add_u32 s12, s12, 0xc000
	s_addc_u32 s13, s13, 0
	s_cmp_lt_u32 s28, 28
	s_cselect_b32 s19, 0x18000, 0
	s_add_u32 s4, s4, s19
	s_addc_u32 s5, s5, 0
	s_cmp_lt_u32 s28, 29
	s_cselect_b32 s19, 0xc000, 0
	s_add_u32 s8, s8, s19
	s_addc_u32 s9, s9, 0
	s_add_u32 s10, s10, s19
	s_addc_u32 s11, s11, 0
	s_cmp_gt_u32 s18, 1
	s_cbranch_scc1 .Lhg_w01_4
	v_mul_f32_e32 v207, 0x3fb8aa3b, v205
	v_exp_f32_e32 v207, v207
	s_nop 0
	ds_write_b32 v26, v207 offset:37888

.Lhg_bfirst_2:
	s_waitcnt vmcnt(9)
	ds_read_b32 v200, v0 offset:57344
	ds_read_b32 v201, v0 offset:57856
	ds_read_b32 v202, v0 offset:58368
	ds_read_b32 v203, v0 offset:58880
	v_lshl_or_b32 v220, v69, 16, v68
	v_lshl_or_b32 v221, v71, 16, v70
	v_lshl_or_b32 v222, v73, 16, v72
	v_lshl_or_b32 v223, v75, 16, v74
	ds_write_b128 v4, v[220:223] offset:27648
	s_waitcnt lgkmcnt(1)
	v_mul_f32_e32 v204, v21, v200
	v_fmac_f32_e32 v204, v22, v201
	v_fmac_f32_e32 v204, v23, v202
	v_add_f32_e32 v205, v200, v201
	v_add_f32_e32 v205, v205, v202
	v_add_f32_e32 v205, v205, v203
	global_load_dword v84, v14, s[4:5]
	global_load_ushort v36, v18, s[8:9]
	global_load_ushort v44, v18, s[10:11]
	v_mov_b32_e32 v219, v52
	v_add_f32_e32 v218, v204, v219
	v_mul_f32_e32 v207, 0x3fb8aa3b, v52
	v_exp_f32_e32 v207, v207
	v_lshlrev_b32_e32 v209, 16, v60
	v_sub_f32_e32 v208, 1.0, v207
	v_mul_f32_e32 v207, 0x3fb8aa3b, v218
	v_exp_f32_e32 v207, v207
	v_add_f32_e32 v206, v218, v24
	v_mul_f32_e32 v224, v209, v207
	v_mul_f32_e32 v206, 0x3fb8aa3b, v206
	v_exp_f32_e32 v206, v206
	v_sub_f32_e32 v207, v205, v218
	v_mul_f32_e32 v52, v209, v206
	v_mul_f32_e32 v207, 0x3fb8aa3b, v207
	v_exp_f32_e32 v207, v207
	v_min_f32_e64 v206, -v218, s29
	v_mul_f32_e32 v210, v208, v207
	v_mul_f32_e32 v206, 0x3fb8aa3b, v206
	v_exp_f32_e32 v206, v206
	s_nop 0
	v_mul_f32_e32 v232, v208, v206
	global_load_dword v85, v14, s[4:5] offset:3072
	global_load_ushort v37, v18, s[8:9] offset:1536
	global_load_ushort v45, v18, s[10:11] offset:1536
	v_add_f32_e32 v219, v219, v53
	v_add_f32_e32 v218, v204, v219
	v_mul_f32_e32 v207, 0x3fb8aa3b, v53
	v_exp_f32_e32 v207, v207
	v_lshlrev_b32_e32 v209, 16, v61
	v_sub_f32_e32 v208, 1.0, v207
	v_mul_f32_e32 v207, 0x3fb8aa3b, v218
	v_exp_f32_e32 v207, v207
	v_add_f32_e32 v206, v218, v24
	v_mul_f32_e32 v225, v209, v207
	v_mul_f32_e32 v206, 0x3fb8aa3b, v206
	v_exp_f32_e32 v206, v206
	v_sub_f32_e32 v207, v205, v218
	v_mul_f32_e32 v53, v209, v206
	v_mul_f32_e32 v207, 0x3fb8aa3b, v207
	v_exp_f32_e32 v207, v207
	v_min_f32_e64 v206, -v218, s29
	v_mul_f32_e32 v211, v208, v207
	v_mul_f32_e32 v206, 0x3fb8aa3b, v206
	v_exp_f32_e32 v206, v206
	s_nop 0
	v_mul_f32_e32 v233, v208, v206
	global_load_dword v86, v15, s[4:5]
	global_load_ushort v38, v18, s[8:9] offset:3072
	global_load_ushort v46, v18, s[10:11] offset:3072
	v_add_f32_e32 v219, v219, v54
	v_add_f32_e32 v218, v204, v219
	v_mul_f32_e32 v207, 0x3fb8aa3b, v54
	v_exp_f32_e32 v207, v207
	v_lshlrev_b32_e32 v209, 16, v62
	v_sub_f32_e32 v208, 1.0, v207
	v_mul_f32_e32 v207, 0x3fb8aa3b, v218
	v_exp_f32_e32 v207, v207
	v_add_f32_e32 v206, v218, v24
	v_mul_f32_e32 v226, v209, v207
	v_mul_f32_e32 v206, 0x3fb8aa3b, v206
	v_exp_f32_e32 v206, v206
	v_sub_f32_e32 v207, v205, v218
	v_mul_f32_e32 v54, v209, v206
	v_mul_f32_e32 v207, 0x3fb8aa3b, v207
	v_exp_f32_e32 v207, v207
	v_min_f32_e64 v206, -v218, s29
	v_mul_f32_e32 v212, v208, v207
	v_mul_f32_e32 v206, 0x3fb8aa3b, v206
	v_exp_f32_e32 v206, v206
	s_nop 0
	v_mul_f32_e32 v234, v208, v206
	global_load_dword v87, v15, s[4:5] offset:3072
	global_load_ushort v39, v19, s[8:9]
	global_load_ushort v47, v19, s[10:11]
	v_add_f32_e32 v219, v219, v55
	v_add_f32_e32 v218, v204, v219
	v_mul_f32_e32 v207, 0x3fb8aa3b, v55
	v_exp_f32_e32 v207, v207
	v_lshlrev_b32_e32 v209, 16, v63
	v_sub_f32_e32 v208, 1.0, v207
	v_mul_f32_e32 v207, 0x3fb8aa3b, v218
	v_exp_f32_e32 v207, v207
	v_add_f32_e32 v206, v218, v24
	v_mul_f32_e32 v227, v209, v207
	v_mul_f32_e32 v206, 0x3fb8aa3b, v206
	v_exp_f32_e32 v206, v206
	v_sub_f32_e32 v207, v205, v218
	v_mul_f32_e32 v55, v209, v206
	v_mul_f32_e32 v207, 0x3fb8aa3b, v207
	v_exp_f32_e32 v207, v207
	v_min_f32_e64 v206, -v218, s29
	v_mul_f32_e32 v213, v208, v207
	v_mul_f32_e32 v206, 0x3fb8aa3b, v206
	v_exp_f32_e32 v206, v206
	s_nop 0
	v_mul_f32_e32 v235, v208, v206
	global_load_dword v88, v16, s[4:5]
	global_load_ushort v40, v19, s[8:9] offset:1536
	global_load_ushort v48, v19, s[10:11] offset:1536
	v_add_f32_e32 v219, v219, v56
	v_add_f32_e32 v218, v204, v219
	v_mul_f32_e32 v207, 0x3fb8aa3b, v56
	v_exp_f32_e32 v207, v207
	v_lshlrev_b32_e32 v209, 16, v64
	v_sub_f32_e32 v208, 1.0, v207
	v_mul_f32_e32 v207, 0x3fb8aa3b, v218
	v_exp_f32_e32 v207, v207
	v_add_f32_e32 v206, v218, v24
	v_mul_f32_e32 v228, v209, v207
	v_mul_f32_e32 v206, 0x3fb8aa3b, v206
	v_exp_f32_e32 v206, v206
	v_sub_f32_e32 v207, v205, v218
	v_mul_f32_e32 v56, v209, v206
	v_mul_f32_e32 v207, 0x3fb8aa3b, v207
	v_exp_f32_e32 v207, v207
	v_min_f32_e64 v206, -v218, s29
	v_mul_f32_e32 v214, v208, v207
	v_mul_f32_e32 v206, 0x3fb8aa3b, v206
	v_exp_f32_e32 v206, v206
	s_nop 0
	v_mul_f32_e32 v236, v208, v206
	global_load_dword v89, v16, s[4:5] offset:3072
	global_load_ushort v41, v19, s[8:9] offset:3072
	global_load_ushort v49, v19, s[10:11] offset:3072
	v_add_f32_e32 v219, v219, v57
	v_add_f32_e32 v218, v204, v219
	v_mul_f32_e32 v207, 0x3fb8aa3b, v57
	v_exp_f32_e32 v207, v207
	v_lshlrev_b32_e32 v209, 16, v65
	v_sub_f32_e32 v208, 1.0, v207
	v_mul_f32_e32 v207, 0x3fb8aa3b, v218
	v_exp_f32_e32 v207, v207
	v_add_f32_e32 v206, v218, v24
	v_mul_f32_e32 v229, v209, v207
	v_mul_f32_e32 v206, 0x3fb8aa3b, v206
	v_exp_f32_e32 v206, v206
	v_sub_f32_e32 v207, v205, v218
	v_mul_f32_e32 v57, v209, v206
	v_mul_f32_e32 v207, 0x3fb8aa3b, v207
	v_exp_f32_e32 v207, v207
	v_min_f32_e64 v206, -v218, s29
	v_mul_f32_e32 v215, v208, v207
	v_mul_f32_e32 v206, 0x3fb8aa3b, v206
	v_exp_f32_e32 v206, v206
	s_nop 0
	v_mul_f32_e32 v237, v208, v206
	global_load_dword v90, v17, s[4:5]
	global_load_ushort v42, v20, s[8:9]
	global_load_ushort v50, v20, s[10:11]
	v_add_f32_e32 v219, v219, v58
	v_add_f32_e32 v218, v204, v219
	v_mul_f32_e32 v207, 0x3fb8aa3b, v58
	v_exp_f32_e32 v207, v207
	v_lshlrev_b32_e32 v209, 16, v66
	v_sub_f32_e32 v208, 1.0, v207
	v_mul_f32_e32 v207, 0x3fb8aa3b, v218
	v_exp_f32_e32 v207, v207
	v_add_f32_e32 v206, v218, v24
	v_mul_f32_e32 v230, v209, v207
	v_mul_f32_e32 v206, 0x3fb8aa3b, v206
	v_exp_f32_e32 v206, v206
	v_sub_f32_e32 v207, v205, v218
	v_mul_f32_e32 v58, v209, v206
	v_mul_f32_e32 v207, 0x3fb8aa3b, v207
	v_exp_f32_e32 v207, v207
	v_min_f32_e64 v206, -v218, s29
	v_mul_f32_e32 v216, v208, v207
	v_mul_f32_e32 v206, 0x3fb8aa3b, v206
	v_exp_f32_e32 v206, v206
	s_nop 0
	v_mul_f32_e32 v238, v208, v206
	global_load_dword v91, v17, s[4:5] offset:3072
	global_load_ushort v43, v20, s[8:9] offset:1536
	global_load_ushort v51, v20, s[10:11] offset:1536
	v_add_f32_e32 v219, v219, v59
	v_add_f32_e32 v218, v204, v219
	v_mul_f32_e32 v207, 0x3fb8aa3b, v59
	v_exp_f32_e32 v207, v207
	v_lshlrev_b32_e32 v209, 16, v67
	v_sub_f32_e32 v208, 1.0, v207
	v_mul_f32_e32 v207, 0x3fb8aa3b, v218
	v_exp_f32_e32 v207, v207
	v_add_f32_e32 v206, v218, v24
	v_mul_f32_e32 v231, v209, v207
	v_mul_f32_e32 v206, 0x3fb8aa3b, v206
	v_exp_f32_e32 v206, v206
	v_sub_f32_e32 v207, v205, v218
	v_mul_f32_e32 v59, v209, v206
	v_mul_f32_e32 v207, 0x3fb8aa3b, v207
	v_exp_f32_e32 v207, v207
	v_min_f32_e64 v206, -v218, s29
	v_mul_f32_e32 v217, v208, v207
	v_mul_f32_e32 v206, 0x3fb8aa3b, v206
	v_exp_f32_e32 v206, v206
	s_nop 0
	v_mul_f32_e32 v239, v208, v206
	v_cvt_pk_bf16_f32 v224, v224, v225
	ds_write_b16 v2, v224
	ds_write_b16_d16_hi v2, v224 offset:272
	v_cvt_pk_bf16_f32 v232, v232, v233
	ds_write_b16 v2, v232 offset:8704
	ds_write_b16_d16_hi v2, v232 offset:8976
	v_cvt_pk_bf16_f32 v226, v226, v227
	ds_write_b16 v2, v226 offset:544
	ds_write_b16_d16_hi v2, v226 offset:816
	v_cvt_pk_bf16_f32 v234, v234, v235
	ds_write_b16 v2, v234 offset:9248
	ds_write_b16_d16_hi v2, v234 offset:9520
	v_cvt_pk_bf16_f32 v228, v228, v229
	ds_write_b16 v2, v228 offset:1088
	ds_write_b16_d16_hi v2, v228 offset:1360
	v_cvt_pk_bf16_f32 v236, v236, v237
	ds_write_b16 v2, v236 offset:9792
	ds_write_b16_d16_hi v2, v236 offset:10064
	v_cvt_pk_bf16_f32 v230, v230, v231
	ds_write_b16 v2, v230 offset:1632
	ds_write_b16_d16_hi v2, v230 offset:1904
	v_cvt_pk_bf16_f32 v238, v238, v239
	ds_write_b16 v2, v238 offset:10336
	ds_write_b16_d16_hi v2, v238 offset:10608
	v_cvt_pk_bf16_f32 v210, v210, v211
	v_cvt_pk_bf16_f32 v211, v212, v213
	v_cvt_pk_bf16_f32 v212, v214, v215
	v_cvt_pk_bf16_f32 v213, v216, v217
	ds_write_b128 v4, v[210:213] offset:17408
	v_cvt_pk_bf16_f32 v52, v52, v53
	v_cvt_pk_bf16_f32 v54, v54, v55
	v_cvt_pk_bf16_f32 v56, v56, v57
	v_cvt_pk_bf16_f32 v58, v58, v59
	global_store_short v18, v52, s[12:13]
	global_store_short_d16_hi v18, v52, s[12:13] offset:1536
	global_store_short v18, v54, s[12:13] offset:3072
	global_store_short_d16_hi v19, v54, s[12:13]
	global_store_short v19, v56, s[12:13] offset:1536
	global_store_short_d16_hi v19, v56, s[12:13] offset:3072
	global_store_short v20, v58, s[12:13]
	global_store_short_d16_hi v20, v58, s[12:13] offset:1536
	s_add_u32 s12, s12, 0xc000
	s_addc_u32 s13, s13, 0
	s_cmp_lt_u32 s28, 28
	s_cselect_b32 s19, 0x18000, 0
	s_add_u32 s4, s4, s19
	s_addc_u32 s5, s5, 0
	s_cmp_lt_u32 s28, 29
	s_cselect_b32 s19, 0xc000, 0
	s_add_u32 s8, s8, s19
	s_addc_u32 s9, s9, 0
	s_add_u32 s10, s10, s19
	s_addc_u32 s11, s11, 0
	s_cmp_gt_u32 s18, 1
	s_cbranch_scc1 .Lhg_w01_5
	v_mul_f32_e32 v207, 0x3fb8aa3b, v205
	v_exp_f32_e32 v207, v207
	s_nop 0
	ds_write_b32 v26, v207 offset:37888

.Lhg_joined_3:
	s_cmp_gt_u32 s28, 29
	s_cbranch_scc1 .Lhg_nop1_6
	s_waitcnt vmcnt(41)
	v_mov_b32_e32 v28, v76
	v_mov_b32_e32 v29, v77
	v_mov_b32_e32 v30, v78
	v_mov_b32_e32 v31, v79
	v_mov_b32_e32 v32, v80
	v_mov_b32_e32 v33, v81
	v_mov_b32_e32 v34, v82
	v_mov_b32_e32 v35, v83
	v_add_f32_e32 v200, v28, v29
	v_add_f32_e32 v200, v200, v30
	v_add_f32_e32 v200, v200, v31
	v_add_f32_e32 v200, v200, v32
	v_add_f32_e32 v200, v200, v33
	v_add_f32_e32 v200, v200, v34
	v_add_f32_e32 v200, v200, v35
	ds_write_b32 v1, v200
.Lhg_nop1_6:
	s_waitcnt lgkmcnt(0)
	s_barrier
	ds_read_b128 v[200:203], v12
	ds_read_b128 v[204:207], v12 offset:16
	s_waitcnt lgkmcnt(0)
	v_cvt_pk_bf16_f32 v200, v200, v201
	v_cvt_pk_bf16_f32 v201, v202, v203
	v_cvt_pk_bf16_f32 v202, v204, v205
	v_cvt_pk_bf16_f32 v203, v206, v207
	global_store_dwordx4 v13, v[200:203], s[14:15]
	s_add_u32 s14, s14, 0x10000
	s_addc_u32 s15, s15, 0
	v_xor_b32_e32 v2, 0x10000, v2
	v_xor_b32_e32 v4, 0x10000, v4
	v_xor_b32_e32 v26, 0x10000, v26
	v_xor_b32_e32 v5, 0x10000, v5
	v_xor_b32_e32 v6, 0x10000, v6
	v_xor_b32_e32 v7, 0x10000, v7
	v_xor_b32_e32 v8, 0x10000, v8
	v_xor_b32_e32 v9, 0x10000, v9
	v_xor_b32_e32 v10, 0x10000, v10
	v_xor_b32_e32 v11, 0x10000, v11
	v_xor_b32_e32 v12, 0x10000, v12
	s_add_i32 s28, s28, 1
	s_cmp_eq_u32 s28, 31
	s_cbranch_scc1 .Lhg_last
	s_cmp_gt_u32 s18, 3
	s_cbranch_scc1 .Lhg_bfirst_7
	ds_read_b128 v[144:147], v5 offset:8704
	ds_read_b128 v[148:151], v5 offset:13056
	ds_read_b128 v[152:155], v5 offset:0
	ds_read_b128 v[172:175], v5 offset:4352
	ds_read_b128 v[176:179], v5 offset:8768
	ds_read_b128 v[180:183], v5 offset:13120
	ds_read_b128 v[184:187], v5 offset:64
	ds_read_b128 v[188:191], v5 offset:4416
	ds_read_b128 v[200:203], v5 offset:8832
	ds_read_b128 v[204:207], v5 offset:13184
	ds_read_b128 v[208:211], v5 offset:128
	ds_read_b128 v[212:215], v5 offset:4480
	s_waitcnt lgkmcnt(8)
	v_mfma_f32_16x16x32_bf16 v[124:127], v[144:147], v[152:155], 0
	v_mfma_f32_16x16x32_bf16 v[128:131], v[144:147], v[172:175], 0
	v_mfma_f32_16x16x32_bf16 v[132:135], v[148:151], v[172:175], 0
	ds_read_b128 v[216:219], v5 offset:8896
	ds_read_b128 v[220:223], v5 offset:13248
	ds_read_b128 v[224:227], v5 offset:192
	ds_read_b128 v[228:231], v5 offset:4544
	s_waitcnt lgkmcnt(8)
	v_mfma_f32_16x16x32_bf16 v[124:127], v[176:179], v[184:187], v[124:127]
	v_mfma_f32_16x16x32_bf16 v[128:131], v[176:179], v[188:191], v[128:131]
	v_mfma_f32_16x16x32_bf16 v[132:135], v[180:183], v[188:191], v[132:135]
	ds_read_b64 v[144:145], v6 offset:0
	ds_read_b64 v[146:147], v6 offset:32
	ds_read_b64 v[148:149], v6 offset:4352
	ds_read_b64 v[150:151], v6 offset:4384
	s_waitcnt lgkmcnt(8)
	v_mfma_f32_16x16x32_bf16 v[124:127], v[200:203], v[208:211], v[124:127]
	v_mfma_f32_16x16x32_bf16 v[128:131], v[200:203], v[212:215], v[128:131]
	v_mfma_f32_16x16x32_bf16 v[132:135], v[204:207], v[212:215], v[132:135]
	ds_read_b64 v[152:153], v6 offset:64
	ds_read_b64 v[154:155], v6 offset:96
	ds_read_b64 v[172:173], v6 offset:4416
	ds_read_b64 v[174:175], v6 offset:4448
	s_waitcnt lgkmcnt(8)
	v_mfma_f32_16x16x32_bf16 v[124:127], v[216:219], v[224:227], v[124:127]
	v_mfma_f32_16x16x32_bf16 v[128:131], v[216:219], v[228:231], v[128:131]
	v_mfma_f32_16x16x32_bf16 v[132:135], v[220:223], v[228:231], v[132:135]
	ds_read_b64 v[176:177], v6 offset:128
	ds_read_b64 v[178:179], v6 offset:160
	ds_read_b64 v[180:181], v6 offset:4480
	ds_read_b64 v[182:183], v6 offset:4512
	v_cvt_pk_bf16_f32 v232, v92, v93
	v_cvt_pk_bf16_f32 v233, v94, v95
	v_cvt_pk_bf16_f32 v234, v96, v97
	v_cvt_pk_bf16_f32 v235, v98, v99
	s_waitcnt lgkmcnt(8)
	s_nop 1
	v_mfma_f32_16x16x32_bf16 v[136:139], v[144:147], v[232:235], 0
	v_mfma_f32_16x16x32_bf16 v[140:143], v[148:151], v[232:235], 0
	ds_read_b64 v[184:185], v6 offset:192
	ds_read_b64 v[186:187], v6 offset:224
	ds_read_b64 v[188:189], v6 offset:4544
	ds_read_b64 v[190:191], v6 offset:4576
	v_cvt_pk_bf16_f32 v232, v100, v101
	v_cvt_pk_bf16_f32 v233, v102, v103
	v_cvt_pk_bf16_f32 v234, v104, v105
	v_cvt_pk_bf16_f32 v235, v106, v107
	s_waitcnt lgkmcnt(8)
	s_nop 1
	v_mfma_f32_16x16x32_bf16 v[136:139], v[152:155], v[232:235], v[136:139]
	v_mfma_f32_16x16x32_bf16 v[140:143], v[172:175], v[232:235], v[140:143]
	ds_read_b64 v[236:237], v7 offset:27648
	ds_read_b64 v[238:239], v7 offset:27680
	ds_read_b128 v[200:203], v8 offset:27648
	v_cvt_pk_bf16_f32 v232, v108, v109
	v_cvt_pk_bf16_f32 v233, v110, v111
	v_cvt_pk_bf16_f32 v234, v112, v113
	v_cvt_pk_bf16_f32 v235, v114, v115
	s_waitcnt lgkmcnt(7)
	s_nop 1
	v_mfma_f32_16x16x32_bf16 v[136:139], v[176:179], v[232:235], v[136:139]
	v_mfma_f32_16x16x32_bf16 v[140:143], v[180:183], v[232:235], v[140:143]
	ds_read_b128 v[204:207], v9 offset:17408
	ds_read_b128 v[208:211], v10 offset:37888
	v_cvt_pk_bf16_f32 v232, v116, v117
	v_cvt_pk_bf16_f32 v233, v118, v119
	v_cvt_pk_bf16_f32 v234, v120, v121
	v_cvt_pk_bf16_f32 v235, v122, v123
	s_waitcnt lgkmcnt(5)
	s_nop 1
	v_mfma_f32_16x16x32_bf16 v[136:139], v[184:187], v[232:235], v[136:139]
	v_mfma_f32_16x16x32_bf16 v[140:143], v[188:191], v[232:235], v[140:143]
	ds_read_b128 v[212:215], v9 offset:18688
	ds_read_b128 v[216:219], v10 offset:37952
	v_cndmask_b32_e64 v124, 0, v124, s[40:41]
	v_cndmask_b32_e64 v132, 0, v132, s[40:41]
	v_cndmask_b32_e64 v125, 0, v125, s[42:43]
	v_cndmask_b32_e64 v133, 0, v133, s[42:43]
	v_cndmask_b32_e64 v126, 0, v126, s[44:45]
	v_cndmask_b32_e64 v134, 0, v134, s[44:45]
	v_cndmask_b32_e64 v127, 0, v127, s[46:47]
	v_cndmask_b32_e64 v135, 0, v135, s[46:47]
	v_cvt_pk_bf16_f32 v124, v124, v125
	v_cvt_pk_bf16_f32 v125, v126, v127
	v_mov_b32_e32 v126, 0
	v_mov_b32_e32 v127, 0
	v_cvt_pk_bf16_f32 v128, v128, v129
	v_cvt_pk_bf16_f32 v129, v130, v131
	v_cvt_pk_bf16_f32 v130, v132, v133
	v_cvt_pk_bf16_f32 v131, v134, v135
	s_waitcnt lgkmcnt(4)
	s_nop 1
	v_mfma_f32_16x16x32_bf16 v[136:139], v[124:127], v[236:239], v[136:139]
	v_mfma_f32_16x16x32_bf16 v[140:143], v[128:131], v[236:239], v[140:143]
	ds_read_b128 v[220:223], v9 offset:19968
	ds_read_b128 v[224:227], v10 offset:38016
	ds_read_b128 v[228:231], v9 offset:21248
	ds_read_b128 v[144:147], v10 offset:38080
	s_waitcnt lgkmcnt(6)
	v_pk_mul_f32 v[92:93], v[92:93], v[208:209]
	v_pk_mul_f32 v[94:95], v[94:95], v[210:211]
	s_nop 1
	v_mfma_f32_16x16x32_bf16 v[92:95], v[204:207], v[200:203], v[92:95]
	ds_read_b128 v[152:155], v9 offset:22528
	ds_read_b128 v[172:175], v10 offset:38144
	s_waitcnt lgkmcnt(6)
	v_pk_mul_f32 v[96:97], v[96:97], v[216:217]
	v_pk_mul_f32 v[98:99], v[98:99], v[218:219]
	s_nop 1
	v_mfma_f32_16x16x32_bf16 v[96:99], v[212:215], v[200:203], v[96:99]
	ds_read_b128 v[176:179], v9 offset:23808
	ds_read_b128 v[180:183], v10 offset:38208
	s_waitcnt lgkmcnt(6)
	v_pk_mul_f32 v[100:101], v[100:101], v[224:225]
	v_pk_mul_f32 v[102:103], v[102:103], v[226:227]
	s_nop 1
	v_mfma_f32_16x16x32_bf16 v[100:103], v[220:223], v[200:203], v[100:103]
	ds_read_b128 v[184:187], v9 offset:25088
	ds_read_b128 v[188:191], v10 offset:38272
	s_waitcnt lgkmcnt(6)
	v_pk_mul_f32 v[104:105], v[104:105], v[144:145]
	v_pk_mul_f32 v[106:107], v[106:107], v[146:147]
	s_nop 1
	v_mfma_f32_16x16x32_bf16 v[104:107], v[228:231], v[200:203], v[104:107]
	ds_read_b128 v[204:207], v9 offset:26368
	ds_read_b128 v[208:211], v10 offset:38336
	s_waitcnt lgkmcnt(6)
	v_pk_mul_f32 v[108:109], v[108:109], v[172:173]
	v_pk_mul_f32 v[110:111], v[110:111], v[174:175]
	s_nop 1
	v_mfma_f32_16x16x32_bf16 v[108:111], v[152:155], v[200:203], v[108:111]
	s_waitcnt lgkmcnt(4)
	v_pk_mul_f32 v[112:113], v[112:113], v[180:181]
	v_pk_mul_f32 v[114:115], v[114:115], v[182:183]
	s_nop 1
	v_mfma_f32_16x16x32_bf16 v[112:115], v[176:179], v[200:203], v[112:115]
	s_waitcnt lgkmcnt(2)
	v_pk_mul_f32 v[116:117], v[116:117], v[188:189]
	v_pk_mul_f32 v[118:119], v[118:119], v[190:191]
	s_nop 1
	v_mfma_f32_16x16x32_bf16 v[116:119], v[184:187], v[200:203], v[116:119]
	s_waitcnt lgkmcnt(0)
	v_pk_mul_f32 v[120:121], v[120:121], v[208:209]
	v_pk_mul_f32 v[122:123], v[122:123], v[210:211]
	s_nop 1
	v_mfma_f32_16x16x32_bf16 v[120:123], v[204:207], v[200:203], v[120:123]
	ds_write_b32 v11, v136
	ds_write_b32 v11, v140 offset:8448
	ds_write_b32 v11, v137 offset:528
	ds_write_b32 v11, v141 offset:8976
	ds_write_b32 v11, v138 offset:1056
	ds_write_b32 v11, v142 offset:9504
	ds_write_b32 v11, v139 offset:1584
	ds_write_b32 v11, v143 offset:10032
	s_waitcnt vmcnt(9)
	ds_read_b32 v200, v0 offset:55296
	ds_read_b32 v201, v0 offset:55808
	ds_read_b32 v202, v0 offset:56320
	ds_read_b32 v203, v0 offset:56832
	v_lshl_or_b32 v220, v45, 16, v44
	v_lshl_or_b32 v221, v47, 16, v46
	v_lshl_or_b32 v222, v49, 16, v48
	v_lshl_or_b32 v223, v51, 16, v50
	ds_write_b128 v4, v[220:223] offset:27648
	s_waitcnt lgkmcnt(1)
	v_mul_f32_e32 v204, v21, v200
	v_fmac_f32_e32 v204, v22, v201
	v_fmac_f32_e32 v204, v23, v202
	v_add_f32_e32 v205, v200, v201
	v_add_f32_e32 v205, v205, v202
	v_add_f32_e32 v205, v205, v203
	global_load_dword v76, v14, s[4:5]
	global_load_ushort v60, v18, s[8:9]
	global_load_ushort v68, v18, s[10:11]
	v_mov_b32_e32 v219, v28
	v_add_f32_e32 v218, v204, v219
	v_mul_f32_e32 v207, 0x3fb8aa3b, v28
	v_exp_f32_e32 v207, v207
	v_lshlrev_b32_e32 v209, 16, v36
	v_sub_f32_e32 v208, 1.0, v207
	v_mul_f32_e32 v207, 0x3fb8aa3b, v218
	v_exp_f32_e32 v207, v207
	v_add_f32_e32 v206, v218, v24
	v_mul_f32_e32 v224, v209, v207
	v_mul_f32_e32 v206, 0x3fb8aa3b, v206
	v_exp_f32_e32 v206, v206
	v_sub_f32_e32 v207, v205, v218
	v_mul_f32_e32 v28, v209, v206
	v_mul_f32_e32 v207, 0x3fb8aa3b, v207
	v_exp_f32_e32 v207, v207
	v_min_f32_e64 v206, -v218, s29
	v_mul_f32_e32 v210, v208, v207
	v_mul_f32_e32 v206, 0x3fb8aa3b, v206
	v_exp_f32_e32 v206, v206
	s_nop 0
	v_mul_f32_e32 v232, v208, v206
	global_load_dword v77, v14, s[4:5] offset:3072
	global_load_ushort v61, v18, s[8:9] offset:1536
	global_load_ushort v69, v18, s[10:11] offset:1536
	v_add_f32_e32 v219, v219, v29
	v_add_f32_e32 v218, v204, v219
	v_mul_f32_e32 v207, 0x3fb8aa3b, v29
	v_exp_f32_e32 v207, v207
	v_lshlrev_b32_e32 v209, 16, v37
	v_sub_f32_e32 v208, 1.0, v207
	v_mul_f32_e32 v207, 0x3fb8aa3b, v218
	v_exp_f32_e32 v207, v207
	v_add_f32_e32 v206, v218, v24
	v_mul_f32_e32 v225, v209, v207
	v_mul_f32_e32 v206, 0x3fb8aa3b, v206
	v_exp_f32_e32 v206, v206
	v_sub_f32_e32 v207, v205, v218
	v_mul_f32_e32 v29, v209, v206
	v_mul_f32_e32 v207, 0x3fb8aa3b, v207
	v_exp_f32_e32 v207, v207
	v_min_f32_e64 v206, -v218, s29
	v_mul_f32_e32 v211, v208, v207
	v_mul_f32_e32 v206, 0x3fb8aa3b, v206
	v_exp_f32_e32 v206, v206
	s_nop 0
	v_mul_f32_e32 v233, v208, v206
	global_load_dword v78, v15, s[4:5]
	global_load_ushort v62, v18, s[8:9] offset:3072
	global_load_ushort v70, v18, s[10:11] offset:3072
	v_add_f32_e32 v219, v219, v30
	v_add_f32_e32 v218, v204, v219
	v_mul_f32_e32 v207, 0x3fb8aa3b, v30
	v_exp_f32_e32 v207, v207
	v_lshlrev_b32_e32 v209, 16, v38
	v_sub_f32_e32 v208, 1.0, v207
	v_mul_f32_e32 v207, 0x3fb8aa3b, v218
	v_exp_f32_e32 v207, v207
	v_add_f32_e32 v206, v218, v24
	v_mul_f32_e32 v226, v209, v207
	v_mul_f32_e32 v206, 0x3fb8aa3b, v206
	v_exp_f32_e32 v206, v206
	v_sub_f32_e32 v207, v205, v218
	v_mul_f32_e32 v30, v209, v206
	v_mul_f32_e32 v207, 0x3fb8aa3b, v207
	v_exp_f32_e32 v207, v207
	v_min_f32_e64 v206, -v218, s29
	v_mul_f32_e32 v212, v208, v207
	v_mul_f32_e32 v206, 0x3fb8aa3b, v206
	v_exp_f32_e32 v206, v206
	s_nop 0
	v_mul_f32_e32 v234, v208, v206
	global_load_dword v79, v15, s[4:5] offset:3072
	global_load_ushort v63, v19, s[8:9]
	global_load_ushort v71, v19, s[10:11]
	v_add_f32_e32 v219, v219, v31
	v_add_f32_e32 v218, v204, v219
	v_mul_f32_e32 v207, 0x3fb8aa3b, v31
	v_exp_f32_e32 v207, v207
	v_lshlrev_b32_e32 v209, 16, v39
	v_sub_f32_e32 v208, 1.0, v207
	v_mul_f32_e32 v207, 0x3fb8aa3b, v218
	v_exp_f32_e32 v207, v207
	v_add_f32_e32 v206, v218, v24
	v_mul_f32_e32 v227, v209, v207
	v_mul_f32_e32 v206, 0x3fb8aa3b, v206
	v_exp_f32_e32 v206, v206
	v_sub_f32_e32 v207, v205, v218
	v_mul_f32_e32 v31, v209, v206
	v_mul_f32_e32 v207, 0x3fb8aa3b, v207
	v_exp_f32_e32 v207, v207
	v_min_f32_e64 v206, -v218, s29
	v_mul_f32_e32 v213, v208, v207
	v_mul_f32_e32 v206, 0x3fb8aa3b, v206
	v_exp_f32_e32 v206, v206
	s_nop 0
	v_mul_f32_e32 v235, v208, v206
	global_load_dword v80, v16, s[4:5]
	global_load_ushort v64, v19, s[8:9] offset:1536
	global_load_ushort v72, v19, s[10:11] offset:1536
	v_add_f32_e32 v219, v219, v32
	v_add_f32_e32 v218, v204, v219
	v_mul_f32_e32 v207, 0x3fb8aa3b, v32
	v_exp_f32_e32 v207, v207
	v_lshlrev_b32_e32 v209, 16, v40
	v_sub_f32_e32 v208, 1.0, v207
	v_mul_f32_e32 v207, 0x3fb8aa3b, v218
	v_exp_f32_e32 v207, v207
	v_add_f32_e32 v206, v218, v24
	v_mul_f32_e32 v228, v209, v207
	v_mul_f32_e32 v206, 0x3fb8aa3b, v206
	v_exp_f32_e32 v206, v206
	v_sub_f32_e32 v207, v205, v218
	v_mul_f32_e32 v32, v209, v206
	v_mul_f32_e32 v207, 0x3fb8aa3b, v207
	v_exp_f32_e32 v207, v207
	v_min_f32_e64 v206, -v218, s29
	v_mul_f32_e32 v214, v208, v207
	v_mul_f32_e32 v206, 0x3fb8aa3b, v206
	v_exp_f32_e32 v206, v206
	s_nop 0
	v_mul_f32_e32 v236, v208, v206
	global_load_dword v81, v16, s[4:5] offset:3072
	global_load_ushort v65, v19, s[8:9] offset:3072
	global_load_ushort v73, v19, s[10:11] offset:3072
	v_add_f32_e32 v219, v219, v33
	v_add_f32_e32 v218, v204, v219
	v_mul_f32_e32 v207, 0x3fb8aa3b, v33
	v_exp_f32_e32 v207, v207
	v_lshlrev_b32_e32 v209, 16, v41
	v_sub_f32_e32 v208, 1.0, v207
	v_mul_f32_e32 v207, 0x3fb8aa3b, v218
	v_exp_f32_e32 v207, v207
	v_add_f32_e32 v206, v218, v24
	v_mul_f32_e32 v229, v209, v207
	v_mul_f32_e32 v206, 0x3fb8aa3b, v206
	v_exp_f32_e32 v206, v206
	v_sub_f32_e32 v207, v205, v218
	v_mul_f32_e32 v33, v209, v206
	v_mul_f32_e32 v207, 0x3fb8aa3b, v207
	v_exp_f32_e32 v207, v207
	v_min_f32_e64 v206, -v218, s29
	v_mul_f32_e32 v215, v208, v207
	v_mul_f32_e32 v206, 0x3fb8aa3b, v206
	v_exp_f32_e32 v206, v206
	s_nop 0
	v_mul_f32_e32 v237, v208, v206
	global_load_dword v82, v17, s[4:5]
	global_load_ushort v66, v20, s[8:9]
	global_load_ushort v74, v20, s[10:11]
	v_add_f32_e32 v219, v219, v34
	v_add_f32_e32 v218, v204, v219
	v_mul_f32_e32 v207, 0x3fb8aa3b, v34
	v_exp_f32_e32 v207, v207
	v_lshlrev_b32_e32 v209, 16, v42
	v_sub_f32_e32 v208, 1.0, v207
	v_mul_f32_e32 v207, 0x3fb8aa3b, v218
	v_exp_f32_e32 v207, v207
	v_add_f32_e32 v206, v218, v24
	v_mul_f32_e32 v230, v209, v207
	v_mul_f32_e32 v206, 0x3fb8aa3b, v206
	v_exp_f32_e32 v206, v206
	v_sub_f32_e32 v207, v205, v218
	v_mul_f32_e32 v34, v209, v206
	v_mul_f32_e32 v207, 0x3fb8aa3b, v207
	v_exp_f32_e32 v207, v207
	v_min_f32_e64 v206, -v218, s29
	v_mul_f32_e32 v216, v208, v207
	v_mul_f32_e32 v206, 0x3fb8aa3b, v206
	v_exp_f32_e32 v206, v206
	s_nop 0
	v_mul_f32_e32 v238, v208, v206
	global_load_dword v83, v17, s[4:5] offset:3072
	global_load_ushort v67, v20, s[8:9] offset:1536
	global_load_ushort v75, v20, s[10:11] offset:1536
	v_add_f32_e32 v219, v219, v35
	v_add_f32_e32 v218, v204, v219
	v_mul_f32_e32 v207, 0x3fb8aa3b, v35
	v_exp_f32_e32 v207, v207
	v_lshlrev_b32_e32 v209, 16, v43
	v_sub_f32_e32 v208, 1.0, v207
	v_mul_f32_e32 v207, 0x3fb8aa3b, v218
	v_exp_f32_e32 v207, v207
	v_add_f32_e32 v206, v218, v24
	v_mul_f32_e32 v231, v209, v207
	v_mul_f32_e32 v206, 0x3fb8aa3b, v206
	v_exp_f32_e32 v206, v206
	v_sub_f32_e32 v207, v205, v218
	v_mul_f32_e32 v35, v209, v206
	v_mul_f32_e32 v207, 0x3fb8aa3b, v207
	v_exp_f32_e32 v207, v207
	v_min_f32_e64 v206, -v218, s29
	v_mul_f32_e32 v217, v208, v207
	v_mul_f32_e32 v206, 0x3fb8aa3b, v206
	v_exp_f32_e32 v206, v206
	s_nop 0
	v_mul_f32_e32 v239, v208, v206
	v_cvt_pk_bf16_f32 v224, v224, v225
	ds_write_b16 v2, v224
	ds_write_b16_d16_hi v2, v224 offset:272
	v_cvt_pk_bf16_f32 v232, v232, v233
	ds_write_b16 v2, v232 offset:8704
	ds_write_b16_d16_hi v2, v232 offset:8976
	v_cvt_pk_bf16_f32 v226, v226, v227
	ds_write_b16 v2, v226 offset:544
	ds_write_b16_d16_hi v2, v226 offset:816
	v_cvt_pk_bf16_f32 v234, v234, v235
	ds_write_b16 v2, v234 offset:9248
	ds_write_b16_d16_hi v2, v234 offset:9520
	v_cvt_pk_bf16_f32 v228, v228, v229
	ds_write_b16 v2, v228 offset:1088
	ds_write_b16_d16_hi v2, v228 offset:1360
	v_cvt_pk_bf16_f32 v236, v236, v237
	ds_write_b16 v2, v236 offset:9792
	ds_write_b16_d16_hi v2, v236 offset:10064
	v_cvt_pk_bf16_f32 v230, v230, v231
	ds_write_b16 v2, v230 offset:1632
	ds_write_b16_d16_hi v2, v230 offset:1904
	v_cvt_pk_bf16_f32 v238, v238, v239
	ds_write_b16 v2, v238 offset:10336
	ds_write_b16_d16_hi v2, v238 offset:10608
	v_cvt_pk_bf16_f32 v210, v210, v211
	v_cvt_pk_bf16_f32 v211, v212, v213
	v_cvt_pk_bf16_f32 v212, v214, v215
	v_cvt_pk_bf16_f32 v213, v216, v217
	ds_write_b128 v4, v[210:213] offset:17408
	v_cvt_pk_bf16_f32 v28, v28, v29
	v_cvt_pk_bf16_f32 v30, v30, v31
	v_cvt_pk_bf16_f32 v32, v32, v33
	v_cvt_pk_bf16_f32 v34, v34, v35
	global_store_short v18, v28, s[12:13]
	global_store_short_d16_hi v18, v28, s[12:13] offset:1536
	global_store_short v18, v30, s[12:13] offset:3072
	global_store_short_d16_hi v19, v30, s[12:13]
	global_store_short v19, v32, s[12:13] offset:1536
	global_store_short_d16_hi v19, v32, s[12:13] offset:3072
	global_store_short v20, v34, s[12:13]
	global_store_short_d16_hi v20, v34, s[12:13] offset:1536
	s_add_u32 s12, s12, 0xc000
	s_addc_u32 s13, s13, 0
	s_cmp_lt_u32 s28, 28
	s_cselect_b32 s19, 0x18000, 0
	s_add_u32 s4, s4, s19
	s_addc_u32 s5, s5, 0
	s_cmp_lt_u32 s28, 29
	s_cselect_b32 s19, 0xc000, 0
	s_add_u32 s8, s8, s19
	s_addc_u32 s9, s9, 0
	s_add_u32 s10, s10, s19
	s_addc_u32 s11, s11, 0
	s_cmp_gt_u32 s18, 1
	s_cbranch_scc1 .Lhg_w01_9
	v_mul_f32_e32 v207, 0x3fb8aa3b, v205
	v_exp_f32_e32 v207, v207
	s_nop 0
	ds_write_b32 v26, v207 offset:37888

.Lhg_bfirst_7:
	s_waitcnt vmcnt(9)
	ds_read_b32 v200, v0 offset:55296
	ds_read_b32 v201, v0 offset:55808
	ds_read_b32 v202, v0 offset:56320
	ds_read_b32 v203, v0 offset:56832
	v_lshl_or_b32 v220, v45, 16, v44
	v_lshl_or_b32 v221, v47, 16, v46
	v_lshl_or_b32 v222, v49, 16, v48
	v_lshl_or_b32 v223, v51, 16, v50
	ds_write_b128 v4, v[220:223] offset:27648
	s_waitcnt lgkmcnt(1)
	v_mul_f32_e32 v204, v21, v200
	v_fmac_f32_e32 v204, v22, v201
	v_fmac_f32_e32 v204, v23, v202
	v_add_f32_e32 v205, v200, v201
	v_add_f32_e32 v205, v205, v202
	v_add_f32_e32 v205, v205, v203
	global_load_dword v76, v14, s[4:5]
	global_load_ushort v60, v18, s[8:9]
	global_load_ushort v68, v18, s[10:11]
	v_mov_b32_e32 v219, v28
	v_add_f32_e32 v218, v204, v219
	v_mul_f32_e32 v207, 0x3fb8aa3b, v28
	v_exp_f32_e32 v207, v207
	v_lshlrev_b32_e32 v209, 16, v36
	v_sub_f32_e32 v208, 1.0, v207
	v_mul_f32_e32 v207, 0x3fb8aa3b, v218
	v_exp_f32_e32 v207, v207
	v_add_f32_e32 v206, v218, v24
	v_mul_f32_e32 v224, v209, v207
	v_mul_f32_e32 v206, 0x3fb8aa3b, v206
	v_exp_f32_e32 v206, v206
	v_sub_f32_e32 v207, v205, v218
	v_mul_f32_e32 v28, v209, v206
	v_mul_f32_e32 v207, 0x3fb8aa3b, v207
	v_exp_f32_e32 v207, v207
	v_min_f32_e64 v206, -v218, s29
	v_mul_f32_e32 v210, v208, v207
	v_mul_f32_e32 v206, 0x3fb8aa3b, v206
	v_exp_f32_e32 v206, v206
	s_nop 0
	v_mul_f32_e32 v232, v208, v206
	global_load_dword v77, v14, s[4:5] offset:3072
	global_load_ushort v61, v18, s[8:9] offset:1536
	global_load_ushort v69, v18, s[10:11] offset:1536
	v_add_f32_e32 v219, v219, v29
	v_add_f32_e32 v218, v204, v219
	v_mul_f32_e32 v207, 0x3fb8aa3b, v29
	v_exp_f32_e32 v207, v207
	v_lshlrev_b32_e32 v209, 16, v37
	v_sub_f32_e32 v208, 1.0, v207
	v_mul_f32_e32 v207, 0x3fb8aa3b, v218
	v_exp_f32_e32 v207, v207
	v_add_f32_e32 v206, v218, v24
	v_mul_f32_e32 v225, v209, v207
	v_mul_f32_e32 v206, 0x3fb8aa3b, v206
	v_exp_f32_e32 v206, v206
	v_sub_f32_e32 v207, v205, v218
	v_mul_f32_e32 v29, v209, v206
	v_mul_f32_e32 v207, 0x3fb8aa3b, v207
	v_exp_f32_e32 v207, v207
	v_min_f32_e64 v206, -v218, s29
	v_mul_f32_e32 v211, v208, v207
	v_mul_f32_e32 v206, 0x3fb8aa3b, v206
	v_exp_f32_e32 v206, v206
	s_nop 0
	v_mul_f32_e32 v233, v208, v206
	global_load_dword v78, v15, s[4:5]
	global_load_ushort v62, v18, s[8:9] offset:3072
	global_load_ushort v70, v18, s[10:11] offset:3072
	v_add_f32_e32 v219, v219, v30
	v_add_f32_e32 v218, v204, v219
	v_mul_f32_e32 v207, 0x3fb8aa3b, v30
	v_exp_f32_e32 v207, v207
	v_lshlrev_b32_e32 v209, 16, v38
	v_sub_f32_e32 v208, 1.0, v207
	v_mul_f32_e32 v207, 0x3fb8aa3b, v218
	v_exp_f32_e32 v207, v207
	v_add_f32_e32 v206, v218, v24
	v_mul_f32_e32 v226, v209, v207
	v_mul_f32_e32 v206, 0x3fb8aa3b, v206
	v_exp_f32_e32 v206, v206
	v_sub_f32_e32 v207, v205, v218
	v_mul_f32_e32 v30, v209, v206
	v_mul_f32_e32 v207, 0x3fb8aa3b, v207
	v_exp_f32_e32 v207, v207
	v_min_f32_e64 v206, -v218, s29
	v_mul_f32_e32 v212, v208, v207
	v_mul_f32_e32 v206, 0x3fb8aa3b, v206
	v_exp_f32_e32 v206, v206
	s_nop 0
	v_mul_f32_e32 v234, v208, v206
	global_load_dword v79, v15, s[4:5] offset:3072
	global_load_ushort v63, v19, s[8:9]
	global_load_ushort v71, v19, s[10:11]
	v_add_f32_e32 v219, v219, v31
	v_add_f32_e32 v218, v204, v219
	v_mul_f32_e32 v207, 0x3fb8aa3b, v31
	v_exp_f32_e32 v207, v207
	v_lshlrev_b32_e32 v209, 16, v39
	v_sub_f32_e32 v208, 1.0, v207
	v_mul_f32_e32 v207, 0x3fb8aa3b, v218
	v_exp_f32_e32 v207, v207
	v_add_f32_e32 v206, v218, v24
	v_mul_f32_e32 v227, v209, v207
	v_mul_f32_e32 v206, 0x3fb8aa3b, v206
	v_exp_f32_e32 v206, v206
	v_sub_f32_e32 v207, v205, v218
	v_mul_f32_e32 v31, v209, v206
	v_mul_f32_e32 v207, 0x3fb8aa3b, v207
	v_exp_f32_e32 v207, v207
	v_min_f32_e64 v206, -v218, s29
	v_mul_f32_e32 v213, v208, v207
	v_mul_f32_e32 v206, 0x3fb8aa3b, v206
	v_exp_f32_e32 v206, v206
	s_nop 0
	v_mul_f32_e32 v235, v208, v206
	global_load_dword v80, v16, s[4:5]
	global_load_ushort v64, v19, s[8:9] offset:1536
	global_load_ushort v72, v19, s[10:11] offset:1536
	v_add_f32_e32 v219, v219, v32
	v_add_f32_e32 v218, v204, v219
	v_mul_f32_e32 v207, 0x3fb8aa3b, v32
	v_exp_f32_e32 v207, v207
	v_lshlrev_b32_e32 v209, 16, v40
	v_sub_f32_e32 v208, 1.0, v207
	v_mul_f32_e32 v207, 0x3fb8aa3b, v218
	v_exp_f32_e32 v207, v207
	v_add_f32_e32 v206, v218, v24
	v_mul_f32_e32 v228, v209, v207
	v_mul_f32_e32 v206, 0x3fb8aa3b, v206
	v_exp_f32_e32 v206, v206
	v_sub_f32_e32 v207, v205, v218
	v_mul_f32_e32 v32, v209, v206
	v_mul_f32_e32 v207, 0x3fb8aa3b, v207
	v_exp_f32_e32 v207, v207
	v_min_f32_e64 v206, -v218, s29
	v_mul_f32_e32 v214, v208, v207
	v_mul_f32_e32 v206, 0x3fb8aa3b, v206
	v_exp_f32_e32 v206, v206
	s_nop 0
	v_mul_f32_e32 v236, v208, v206
	global_load_dword v81, v16, s[4:5] offset:3072
	global_load_ushort v65, v19, s[8:9] offset:3072
	global_load_ushort v73, v19, s[10:11] offset:3072
	v_add_f32_e32 v219, v219, v33
	v_add_f32_e32 v218, v204, v219
	v_mul_f32_e32 v207, 0x3fb8aa3b, v33
	v_exp_f32_e32 v207, v207
	v_lshlrev_b32_e32 v209, 16, v41
	v_sub_f32_e32 v208, 1.0, v207
	v_mul_f32_e32 v207, 0x3fb8aa3b, v218
	v_exp_f32_e32 v207, v207
	v_add_f32_e32 v206, v218, v24
	v_mul_f32_e32 v229, v209, v207
	v_mul_f32_e32 v206, 0x3fb8aa3b, v206
	v_exp_f32_e32 v206, v206
	v_sub_f32_e32 v207, v205, v218
	v_mul_f32_e32 v33, v209, v206
	v_mul_f32_e32 v207, 0x3fb8aa3b, v207
	v_exp_f32_e32 v207, v207
	v_min_f32_e64 v206, -v218, s29
	v_mul_f32_e32 v215, v208, v207
	v_mul_f32_e32 v206, 0x3fb8aa3b, v206
	v_exp_f32_e32 v206, v206
	s_nop 0
	v_mul_f32_e32 v237, v208, v206
	global_load_dword v82, v17, s[4:5]
	global_load_ushort v66, v20, s[8:9]
	global_load_ushort v74, v20, s[10:11]
	v_add_f32_e32 v219, v219, v34
	v_add_f32_e32 v218, v204, v219
	v_mul_f32_e32 v207, 0x3fb8aa3b, v34
	v_exp_f32_e32 v207, v207
	v_lshlrev_b32_e32 v209, 16, v42
	v_sub_f32_e32 v208, 1.0, v207
	v_mul_f32_e32 v207, 0x3fb8aa3b, v218
	v_exp_f32_e32 v207, v207
	v_add_f32_e32 v206, v218, v24
	v_mul_f32_e32 v230, v209, v207
	v_mul_f32_e32 v206, 0x3fb8aa3b, v206
	v_exp_f32_e32 v206, v206
	v_sub_f32_e32 v207, v205, v218
	v_mul_f32_e32 v34, v209, v206
	v_mul_f32_e32 v207, 0x3fb8aa3b, v207
	v_exp_f32_e32 v207, v207
	v_min_f32_e64 v206, -v218, s29
	v_mul_f32_e32 v216, v208, v207
	v_mul_f32_e32 v206, 0x3fb8aa3b, v206
	v_exp_f32_e32 v206, v206
	s_nop 0
	v_mul_f32_e32 v238, v208, v206
	global_load_dword v83, v17, s[4:5] offset:3072
	global_load_ushort v67, v20, s[8:9] offset:1536
	global_load_ushort v75, v20, s[10:11] offset:1536
	v_add_f32_e32 v219, v219, v35
	v_add_f32_e32 v218, v204, v219
	v_mul_f32_e32 v207, 0x3fb8aa3b, v35
	v_exp_f32_e32 v207, v207
	v_lshlrev_b32_e32 v209, 16, v43
	v_sub_f32_e32 v208, 1.0, v207
	v_mul_f32_e32 v207, 0x3fb8aa3b, v218
	v_exp_f32_e32 v207, v207
	v_add_f32_e32 v206, v218, v24
	v_mul_f32_e32 v231, v209, v207
	v_mul_f32_e32 v206, 0x3fb8aa3b, v206
	v_exp_f32_e32 v206, v206
	v_sub_f32_e32 v207, v205, v218
	v_mul_f32_e32 v35, v209, v206
	v_mul_f32_e32 v207, 0x3fb8aa3b, v207
	v_exp_f32_e32 v207, v207
	v_min_f32_e64 v206, -v218, s29
	v_mul_f32_e32 v217, v208, v207
	v_mul_f32_e32 v206, 0x3fb8aa3b, v206
	v_exp_f32_e32 v206, v206
	s_nop 0
	v_mul_f32_e32 v239, v208, v206
	v_cvt_pk_bf16_f32 v224, v224, v225
	ds_write_b16 v2, v224
	ds_write_b16_d16_hi v2, v224 offset:272
	v_cvt_pk_bf16_f32 v232, v232, v233
	ds_write_b16 v2, v232 offset:8704
	ds_write_b16_d16_hi v2, v232 offset:8976
	v_cvt_pk_bf16_f32 v226, v226, v227
	ds_write_b16 v2, v226 offset:544
	ds_write_b16_d16_hi v2, v226 offset:816
	v_cvt_pk_bf16_f32 v234, v234, v235
	ds_write_b16 v2, v234 offset:9248
	ds_write_b16_d16_hi v2, v234 offset:9520
	v_cvt_pk_bf16_f32 v228, v228, v229
	ds_write_b16 v2, v228 offset:1088
	ds_write_b16_d16_hi v2, v228 offset:1360
	v_cvt_pk_bf16_f32 v236, v236, v237
	ds_write_b16 v2, v236 offset:9792
	ds_write_b16_d16_hi v2, v236 offset:10064
	v_cvt_pk_bf16_f32 v230, v230, v231
	ds_write_b16 v2, v230 offset:1632
	ds_write_b16_d16_hi v2, v230 offset:1904
	v_cvt_pk_bf16_f32 v238, v238, v239
	ds_write_b16 v2, v238 offset:10336
	ds_write_b16_d16_hi v2, v238 offset:10608
	v_cvt_pk_bf16_f32 v210, v210, v211
	v_cvt_pk_bf16_f32 v211, v212, v213
	v_cvt_pk_bf16_f32 v212, v214, v215
	v_cvt_pk_bf16_f32 v213, v216, v217
	ds_write_b128 v4, v[210:213] offset:17408
	v_cvt_pk_bf16_f32 v28, v28, v29
	v_cvt_pk_bf16_f32 v30, v30, v31
	v_cvt_pk_bf16_f32 v32, v32, v33
	v_cvt_pk_bf16_f32 v34, v34, v35
	global_store_short v18, v28, s[12:13]
	global_store_short_d16_hi v18, v28, s[12:13] offset:1536
	global_store_short v18, v30, s[12:13] offset:3072
	global_store_short_d16_hi v19, v30, s[12:13]
	global_store_short v19, v32, s[12:13] offset:1536
	global_store_short_d16_hi v19, v32, s[12:13] offset:3072
	global_store_short v20, v34, s[12:13]
	global_store_short_d16_hi v20, v34, s[12:13] offset:1536
	s_add_u32 s12, s12, 0xc000
	s_addc_u32 s13, s13, 0
	s_cmp_lt_u32 s28, 28
	s_cselect_b32 s19, 0x18000, 0
	s_add_u32 s4, s4, s19
	s_addc_u32 s5, s5, 0
	s_cmp_lt_u32 s28, 29
	s_cselect_b32 s19, 0xc000, 0
	s_add_u32 s8, s8, s19
	s_addc_u32 s9, s9, 0
	s_add_u32 s10, s10, s19
	s_addc_u32 s11, s11, 0
	s_cmp_gt_u32 s18, 1
	s_cbranch_scc1 .Lhg_w01_10
	v_mul_f32_e32 v207, 0x3fb8aa3b, v205
	v_exp_f32_e32 v207, v207
	s_nop 0
	ds_write_b32 v26, v207 offset:37888

.Lhg_joined_8:
	s_cmp_gt_u32 s28, 29
	s_cbranch_scc1 .Lhg_nop1_11
	s_waitcnt vmcnt(41)
	v_mov_b32_e32 v52, v84
	v_mov_b32_e32 v53, v85
	v_mov_b32_e32 v54, v86
	v_mov_b32_e32 v55, v87
	v_mov_b32_e32 v56, v88
	v_mov_b32_e32 v57, v89
	v_mov_b32_e32 v58, v90
	v_mov_b32_e32 v59, v91
	v_add_f32_e32 v200, v52, v53
	v_add_f32_e32 v200, v200, v54
	v_add_f32_e32 v200, v200, v55
	v_add_f32_e32 v200, v200, v56
	v_add_f32_e32 v200, v200, v57
	v_add_f32_e32 v200, v200, v58
	v_add_f32_e32 v200, v200, v59
	ds_write_b32 v1, v200 offset:2048
